# v6 + panel-local sync replaces grid barriers after both out-proj+LN phases (8 same-XCD WGs per row panel; split arrive/wait around w_in_b transposes; pp tiles self-produced; WAR guard on d_out)
# speedup vs baseline: 1.0196x; 1.0122x over previous
; #define LAS __attribute__((address_space(3)))
; __device__ __forceinline__ unsigned xb_add(unsigned* p, unsigned v) { return __hip_atomic_fetch_add(p, v, __ATOMIC_RELAXED, __HIP_MEMORY_SCOPE_AGENT); }
; __device__ __forceinline__ unsigned xb_xcc_id() { return (unsigned)__builtin_amdgcn_s_getreg((3 << 11) | 20) & 0xFu; }
; __device__ __forceinline__ XcdBarrier xcd_barrier_post(unsigned* bar, volatile LAS unsigned* st) {
;     XcdBarrier b; b.bar = bar; b.x = xb_xcc_id(); b.st = st;
;     if (threadIdx.x == 0) (void)xb_add(&bar[XB_XCNT(b.x)], 1u);
;     return b;
; }
.LBB0_2:
	s_or_b64 exec, exec, s[4:5]
	s_waitcnt lgkmcnt(0)
	s_add_u32 s54, s40, 0x3d00000
	s_addc_u32 s55, s41, 0
	s_sub_i32 s3, s43, s42
	s_cmp_lt_i32 s3, 2
	s_barrier
	s_cbranch_scc1 .LBB0_7
	s_getreg_b32 s3, hwreg(HW_REG_XCC_ID, 0, 4)
	s_and_b32 s33, s3, 15
	s_and_saveexec_b64 s[4:5], s[12:13]
	s_cbranch_execz .LBB0_6
	s_mov_b64 s[8:9], exec
	v_mbcnt_lo_u32_b32 v1, s8, 0
	v_mbcnt_hi_u32_b32 v1, s9, v1
	v_cmp_eq_u32_e32 vcc, 0, v1
	s_and_b64 s[10:11], exec, vcc
	s_mov_b64 exec, s[10:11]
	s_cbranch_execz .LBB0_6
	s_lshl_b32 s3, s33, 8
	s_bcnt1_i32_b64 s8, s[8:9]
	v_mov_b32_e32 v1, s3
	v_mov_b32_e32 v2, s8
	global_atomic_add v1, v2, s[54:55] offset:1024
	s_and_b32 s3, s2, 7
	s_lshl_b32 s3, s3, 2
	s_bfe_u32 s8, s2, 0x20003
	s_or_b32 s3, s3, s8
	s_lshl_b32 s3, s3, 6
	s_add_i32 s3, s3, 0xa400
	v_mov_b32_e32 v1, s3
	s_lshl_b32 s8, 1, s33
	v_mov_b32_e32 v2, s8
	global_atomic_or v1, v2, s[54:55] offset:8

; #define PG8_STAGE(bufoff, gbase, voff) do { _Pragma("unroll") for (int _i = 0; _i < 2; ++_i) \
;         __builtin_amdgcn_global_load_lds((const unsigned*)((const char*)(gbase) + (voff)[_i]), (LAS unsigned*)(lds + (bufoff) + ldsw + _i * 8192), 16, 0, 0); } while (0)
; #define PG8_WAIT_V(n) asm volatile("s_waitcnt vmcnt(" #n ")" ::: "memory")
; #define PG8_BAR __builtin_amdgcn_s_barrier()
;     __device__ bool next(int i, Unit& u) const {
;         const long L = (long)i * G + c; if (L >= nwg) return false;
;         int wgid = (int)L; { const int q = nwg / NXCD, r = nwg % NXCD, xcd = wgid % NXCD, off = wgid / NXCD; wgid = (xcd < r ? xcd * (q + 1) : r * (q + 1) + (xcd - r) * q) + off; }
;         const int nig = WGM * nN, gid = wgid / nig, fm = gid * WGM, gsz = (nM - fm) < WGM ? (nM - fm) : WGM;
;         u.pm = fm + ((wgid % nig) % gsz); u.pn = (wgid % nig) / gsz; return true;
; template <class Epi, bool ALIGN_EPI = false, bool SP2 = true>
; __device__ __forceinline__ void gemm_phase(LAS unsigned char* lds, const Gemm g, const StaticOrder& S, const Epi& E) {
;     ...
;     const char* cA = (const char*)g.A + (size_t)cur.pm * tstep; const char* cB = (const char*)g.Bt + (size_t)(cur.pn + (cur.pm >= g.bsplit ? g.badd : 0)) * tstep;
;     if constexpr (SP2) {
;         PG8_STAGE(PG8_SB(0, 0), cB, voffB); PG8_STAGE(PG8_SB(0, 1), cB + hstep, voffB); PG8_STAGE(PG8_SA(0, 0), cA, voffA); PG8_STAGE(PG8_SA(0, 1), cA + hstep, voffA);
;         if (wr == 1) PG8_BAR;
;         PG8_WAIT_V(2); PG8_BAR;
;         PG8_STAGE(PG8_SB(1, 0), cB + kstep, voffB); PG8_STAGE(PG8_SA(1, 0), cA + kstep, voffA); PG8_STAGE(PG8_SB(1, 1), cB + hstep + kstep, voffB);
;         PG8_WAIT_V(6); PG8_BAR;
.LBB0_297:
	s_lshr_b32 s0, s68, 6
	s_ashr_i32 s1, s4, 3
	s_lshr_b32 s4, s68, 8
	s_lshl_b32 s69, s0, 10
	s_add_u32 s70, s40, 0x3200000
	s_addc_u32 s71, s41, 0
	s_add_i32 s1, s5, s1
	s_ashr_i32 s5, s1, 31
	s_lshr_b32 s5, s5, 27
	s_add_i32 s5, s1, s5
	s_ashr_i32 s6, s5, 5
	s_andn2_b32 s5, s5, 31
	s_sub_i32 s1, s1, s5
	s_bfe_i32 s5, s1, 0x80000
	s_bfe_u32 s5, s5, 0x2000d
	s_add_i32 s5, s1, s5
	s_bfe_i32 s7, s5, 0x80000
	s_and_b32 s5, s5, 0xfc
	s_sub_i32 s1, s1, s5
	s_lshl_b32 s6, s6, 2
	s_sext_i32_i8 s1, s1
	s_add_i32 s36, s6, s1
	s_and_b32 s36, s2, 7
	s_lshl_b32 s36, s36, 2
	s_bfe_u32 s1, s2, 0x20003
	s_or_b32 s36, s36, s1
	s_sext_i32_i16 s7, s7
	s_ashr_i32 s37, s36, 31
	s_ashr_i32 s84, s7, 2
	s_lshr_b32 s84, s2, 5
	s_lshl_b64 s[6:7], s[36:37], 17
	s_cmp_gt_i32 s36, 31
	s_cselect_b32 s1, 8, 0
	s_add_i32 s18, s1, s84
	s_ashr_i32 s19, s18, 31
	s_lshl_b64 s[18:19], s[18:19], 17
	s_add_u32 s62, s58, s18
	s_addc_u32 s63, s59, s19
	s_add_i32 s37, s69, 0
	v_lshl_or_b32 v42, v64, 9, v62
	s_add_i32 m0, s37, 0x10000
	v_lshl_or_b32 v46, v66, 9, v62
	global_load_lds_dwordx4 v42, s[62:63]
	s_add_i32 m0, s37, 0x12000
	s_add_u32 s18, s62, 0x10000
	global_load_lds_dwordx4 v46, s[62:63]
	s_addc_u32 s19, s63, 0
	s_add_i32 m0, s37, 0x14000
	v_lshl_or_b32 v40, v63, 9, v62
	global_load_lds_dwordx4 v42, s[18:19]
	s_add_i32 m0, s37, 0x16000
	s_add_u32 s60, s70, s6
	s_addc_u32 s61, s71, s7
	s_add_i32 s72, s37, 0x2000
	global_load_lds_dwordx4 v46, s[18:19]
	s_mov_b32 m0, s37
	s_add_u32 s6, s60, 0x10000
	v_lshl_or_b32 v44, v65, 9, v62
	global_load_lds_dwordx4 v40, s[60:61]
	s_mov_b32 m0, s72
	s_addc_u32 s7, s61, 0
	s_add_i32 s73, s37, 0x4000
	global_load_lds_dwordx4 v44, s[60:61]
	s_mov_b32 m0, s73
	s_add_i32 s74, s37, 0x6000
	global_load_lds_dwordx4 v40, s[6:7]
	s_mov_b32 m0, s74
	v_mov_b32_e32 v43, 0
	global_load_lds_dwordx4 v44, s[6:7]
	v_mov_b32_e32 v47, v43
	v_mov_b32_e32 v41, v43
	v_mov_b32_e32 v45, v43
	v_lshl_add_u64 v[6:7], s[62:63], 0, v[42:43]
	v_lshl_add_u64 v[4:5], s[62:63], 0, v[46:47]
	v_lshl_add_u64 v[2:3], s[60:61], 0, v[40:41]
	s_cmp_lg_u32 s4, 1
	v_lshl_add_u64 v[0:1], s[60:61], 0, v[44:45]
	s_cbranch_scc1 .LBB0_299
	s_barrier

; #define PG8_STAGE(bufoff, gbase, voff) do { _Pragma("unroll") for (int _i = 0; _i < 2; ++_i) \
;         __builtin_amdgcn_global_load_lds((const unsigned*)((const char*)(gbase) + (voff)[_i]), (LAS unsigned*)(lds + (bufoff) + ldsw + _i * 8192), 16, 0, 0); } while (0)
; #define PG8_LDA(dst, b, h) do { _Pragma("unroll") for (int m = 0; m < 4; ++m) _Pragma("unroll") for (int k = 0; k < 2; ++k) dst[m][k] = *(const LAS bf16x8*)(lds + PG8_SA(b, h) + aoff + m * 2048 + k * 1024); } while (0)
; #define PG8_LDB(dst, b, h) do { _Pragma("unroll") for (int n = 0; n < 2; ++n) _Pragma("unroll") for (int k = 0; k < 2; ++k) dst[n][k] = *(const LAS bf16x8*)(lds + PG8_SB(b, h) + boff + n * 2048 + k * 1024); } while (0)
; #define PG8_WAIT_V(n) asm volatile("s_waitcnt vmcnt(" #n ")" ::: "memory")
; #define PG8_WAIT_L(n) asm volatile("s_waitcnt lgkmcnt(" #n ")" ::: "memory")
; #define PG8_BAR __builtin_amdgcn_s_barrier()
; #define PG8_SCHED __builtin_amdgcn_sched_barrier(0)
; template <class Epi, bool ALIGN_EPI = false, bool SP2 = true>
; __device__ __forceinline__ void gemm_phase(LAS unsigned char* lds, const Gemm g, const StaticOrder& S, const Epi& E) {
;     ...
;         const bool has_next = S.next(ui + 1, nxt);
;         const char* nA = has_next ? (const char*)g.A + (size_t)nxt.pm * tstep : cA; const char* nB = has_next ? (const char*)g.Bt + (size_t)(nxt.pn + (nxt.pm >= g.bsplit ? g.badd : 0)) * tstep : cB;
;         for (int t = 0; t < nt; t += 2) {
;             const bool last = (t == nt - 2);
;             const char* a1 = cA + (size_t)(t + 1) * kstep;
;             const char* a2 = last ? nA : cA + (size_t)(t + 2) * kstep; const char* b2 = last ? nB : cB + (size_t)(t + 2) * kstep;
;             const char* a3 = a2 + kstep; const char* b3 = b2 + kstep;
;             if constexpr (SP2) {
;             PG8_LDB(B0, 0, 0); PG8_LDB(B1, 0, 1); PG8_SCHED; PG8_LDA(At, 0, 0); PG8_STAGE(PG8_SA(1, 1), a1 + hstep, voffA);
;             PG8_WAIT_V(8); PG8_WAIT_L(0); PG8_BAR; PG8_MMA(0, 0, At, B0); PG8_MMA(0, 1, At, B1); PG8_BAR; PG8_SCHED;
;             PG8_LDA(At, 0, 1); PG8_STAGE(PG8_SB(0, 0), b2, voffB); PG8_STAGE(PG8_SB(0, 1), b2 + hstep, voffB); PG8_STAGE(PG8_SA(0, 0), a2, voffA);
;             PG8_WAIT_V(8); PG8_WAIT_L(0); PG8_BAR; PG8_MMA(1, 0, At, B0); PG8_MMA(1, 1, At, B1); PG8_BAR; PG8_SCHED;
.LBB0_301:
	s_add_i32 s24, s36, 32
	s_mov_b32 s3, s84
	s_ashr_i32 s25, s24, 31
	s_lshl_b64 s[26:27], s[24:25], 17
	s_add_u32 s26, s70, s26
	ds_read_b128 v[0:3], v70
	ds_read_b128 v[4:7], v70 offset:1024
	ds_read_b128 v[8:11], v70 offset:2048
	ds_read_b128 v[12:15], v70 offset:3072
	ds_read_b128 v[16:19], v71
	ds_read_b128 v[20:23], v71 offset:1024
	ds_read_b128 v[24:27], v71 offset:2048
	ds_read_b128 v[28:31], v71 offset:3072
	v_cmp_lt_i64_e32 vcc, s[22:23], v[48:49]
	s_addc_u32 s27, s71, s27
	s_and_b64 s[28:29], vcc, exec
	s_cselect_b32 s67, s27, s61
	s_cselect_b32 s66, s26, s60
	s_cmp_gt_i32 s24, 31
	s_cselect_b32 s25, 8, 0
	s_add_i32 s28, s25, s3
	s_ashr_i32 s29, s28, 31
	s_lshl_b64 s[28:29], s[28:29], 17
	s_add_u32 s28, s58, s28
	s_addc_u32 s29, s59, s29
	s_and_b64 s[64:65], vcc, exec
	s_cselect_b32 s65, s29, s63
	s_cselect_b32 s64, s28, s62
	s_add_u32 s86, s60, 0x10080
	s_addc_u32 s87, s61, 0
	s_mov_b32 m0, s81
	v_lshl_add_u64 v[94:95], s[86:87], 0, v[40:41]
	ds_read_b128 v[32:35], v72
	ds_read_b128 v[36:39], v72 offset:1024
	ds_read_b128 v[52:55], v72 offset:2048
	ds_read_b128 v[74:77], v72 offset:3072
	ds_read_b128 v[78:81], v72 offset:4096
	ds_read_b128 v[82:85], v72 offset:5120
	ds_read_b128 v[86:89], v72 offset:6144
	ds_read_b128 v[90:93], v72 offset:7168
	global_load_lds_dwordx4 v[94:95], off
	v_lshl_add_u64 v[94:95], s[86:87], 0, v[44:45]
	s_mov_b32 m0, s82
	s_nop 0
	global_load_lds_dwordx4 v[94:95], off
	s_waitcnt vmcnt(8)
	s_waitcnt lgkmcnt(0)
	s_barrier
	s_setprio 1
	s_waitcnt lgkmcnt(0)
	v_mfma_f32_16x16x32_bf16 v[94:97], v[0:3], v[32:35], 0
	v_mfma_f32_16x16x32_bf16 v[98:101], v[8:11], v[32:35], 0
	v_mfma_f32_16x16x32_bf16 v[102:105], v[0:3], v[52:55], 0
	v_mfma_f32_16x16x32_bf16 v[106:109], v[8:11], v[52:55], 0
	v_mfma_f32_16x16x32_bf16 v[110:113], v[0:3], v[78:81], 0
	v_mfma_f32_16x16x32_bf16 v[114:117], v[8:11], v[78:81], 0
	v_mfma_f32_16x16x32_bf16 v[118:121], v[0:3], v[86:89], 0
	v_mfma_f32_16x16x32_bf16 v[122:125], v[8:11], v[86:89], 0
	v_mfma_f32_16x16x32_bf16 v[94:97], v[4:7], v[36:39], v[94:97]
	v_mfma_f32_16x16x32_bf16 v[98:101], v[12:15], v[36:39], v[98:101]
	v_mfma_f32_16x16x32_bf16 v[102:105], v[4:7], v[74:77], v[102:105]
	v_mfma_f32_16x16x32_bf16 v[106:109], v[12:15], v[74:77], v[106:109]
	v_mfma_f32_16x16x32_bf16 v[110:113], v[4:7], v[82:85], v[110:113]
	v_mfma_f32_16x16x32_bf16 v[114:117], v[12:15], v[82:85], v[114:117]
	v_mfma_f32_16x16x32_bf16 v[118:121], v[4:7], v[90:93], v[118:121]
	v_mfma_f32_16x16x32_bf16 v[122:125], v[12:15], v[90:93], v[122:125]
	s_setprio 0
	s_setprio 1
	v_mfma_f32_16x16x32_bf16 v[126:129], v[16:19], v[32:35], 0
	v_mfma_f32_16x16x32_bf16 v[32:35], v[24:27], v[32:35], 0
	v_mfma_f32_16x16x32_bf16 v[126:129], v[20:23], v[36:39], v[126:129]
	v_mfma_f32_16x16x32_bf16 v[32:35], v[28:31], v[36:39], v[32:35]
	v_mfma_f32_16x16x32_bf16 v[36:39], v[16:19], v[52:55], 0
	v_mfma_f32_16x16x32_bf16 v[52:55], v[24:27], v[52:55], 0
	v_mfma_f32_16x16x32_bf16 v[36:39], v[20:23], v[74:77], v[36:39]
	v_mfma_f32_16x16x32_bf16 v[52:55], v[28:31], v[74:77], v[52:55]
	v_mfma_f32_16x16x32_bf16 v[74:77], v[16:19], v[78:81], 0
	v_mfma_f32_16x16x32_bf16 v[78:81], v[24:27], v[78:81], 0
	v_mfma_f32_16x16x32_bf16 v[74:77], v[20:23], v[82:85], v[74:77]
	v_mfma_f32_16x16x32_bf16 v[78:81], v[28:31], v[82:85], v[78:81]
	v_mfma_f32_16x16x32_bf16 v[82:85], v[16:19], v[86:89], 0
	v_mfma_f32_16x16x32_bf16 v[86:89], v[24:27], v[86:89], 0
	v_mfma_f32_16x16x32_bf16 v[82:85], v[20:23], v[90:93], v[82:85]
	v_mfma_f32_16x16x32_bf16 v[86:89], v[28:31], v[90:93], v[86:89]
	s_setprio 0
	s_barrier
	v_lshl_add_u64 v[146:147], s[62:63], 0, v[42:43]
	s_mov_b32 m0, s83
	v_lshl_add_u64 v[162:163], v[146:147], 0, s[6:7]
	s_add_i32 s25, s83, 0x2000
	ds_read_b128 v[90:93], v72 offset:16384
	ds_read_b128 v[130:133], v72 offset:17408
	ds_read_b128 v[134:137], v72 offset:18432
	ds_read_b128 v[138:141], v72 offset:19456
	ds_read_b128 v[142:145], v72 offset:20480
	ds_read_b128 v[150:153], v72 offset:21504
	ds_read_b128 v[154:157], v72 offset:22528
	ds_read_b128 v[158:161], v72 offset:23552
	global_load_lds_dwordx4 v[162:163], off
	v_lshl_add_u64 v[162:163], s[62:63], 0, v[46:47]
	s_add_u32 s86, s62, 0x10100
	v_lshl_add_u64 v[166:167], v[162:163], 0, s[6:7]
	s_mov_b32 m0, s25
	s_addc_u32 s87, s63, 0
	s_add_i32 s85, s80, s69
	global_load_lds_dwordx4 v[166:167], off
	v_lshl_add_u64 v[166:167], s[86:87], 0, v[42:43]
	s_mov_b32 m0, s85
	v_lshl_add_u64 v[232:233], s[60:61], 0, v[40:41]
	global_load_lds_dwordx4 v[166:167], off
	v_lshl_add_u64 v[166:167], s[86:87], 0, v[46:47]
	s_add_i32 s86, s85, 0x2000
	s_mov_b32 m0, s86
	v_lshl_add_u64 v[234:235], s[60:61], 0, v[44:45]
	global_load_lds_dwordx4 v[166:167], off
	v_lshl_add_u64 v[166:167], v[232:233], 0, s[6:7]
	s_mov_b32 m0, s37
	s_nop 0
	global_load_lds_dwordx4 v[166:167], off
	v_lshl_add_u64 v[166:167], v[234:235], 0, s[6:7]
	s_mov_b32 m0, s72
	s_nop 0
	global_load_lds_dwordx4 v[166:167], off
	s_waitcnt vmcnt(8)
	s_waitcnt lgkmcnt(0)
	s_barrier
; #define PG8_STAGE(bufoff, gbase, voff) do { _Pragma("unroll") for (int _i = 0; _i < 2; ++_i) \
;         __builtin_amdgcn_global_load_lds((const unsigned*)((const char*)(gbase) + (voff)[_i]), (LAS unsigned*)(lds + (bufoff) + ldsw + _i * 8192), 16, 0, 0); } while (0)
; #define PG8_LDA(dst, b, h) do { _Pragma("unroll") for (int m = 0; m < 4; ++m) _Pragma("unroll") for (int k = 0; k < 2; ++k) dst[m][k] = *(const LAS bf16x8*)(lds + PG8_SA(b, h) + aoff + m * 2048 + k * 1024); } while (0)
; #define PG8_LDB(dst, b, h) do { _Pragma("unroll") for (int n = 0; n < 2; ++n) _Pragma("unroll") for (int k = 0; k < 2; ++k) dst[n][k] = *(const LAS bf16x8*)(lds + PG8_SB(b, h) + boff + n * 2048 + k * 1024); } while (0)
; #define PG8_MMA(ai, bj, At, Bt) do { __builtin_amdgcn_s_setprio(1); _Pragma("unroll") for (int m = 0; m < 4; ++m) _Pragma("unroll") for (int n = 0; n < 2; ++n) _Pragma("unroll") for (int k = 0; k < 2; ++k) \
;         acc[ai][bj][m][n] = __builtin_amdgcn_mfma_f32_16x16x32_bf16(Bt[n][k], At[m][k], acc[ai][bj][m][n], 0, 0, 0); __builtin_amdgcn_s_setprio(0); } while (0)
; #define PG8_WAIT_V(n) asm volatile("s_waitcnt vmcnt(" #n ")" ::: "memory")
; #define PG8_WAIT_L(n) asm volatile("s_waitcnt lgkmcnt(" #n ")" ::: "memory")
; #define PG8_BAR __builtin_amdgcn_s_barrier()
; #define PG8_SCHED __builtin_amdgcn_sched_barrier(0)
; template <class Epi, bool ALIGN_EPI = false, bool SP2 = true>
; __device__ __forceinline__ void gemm_phase(LAS unsigned char* lds, const Gemm g, const StaticOrder& S, const Epi& E) {
;     ...
;             PG8_WAIT_V(8); PG8_WAIT_L(0); PG8_BAR; PG8_MMA(0, 0, At, B0); PG8_MMA(0, 1, At, B1); PG8_BAR; PG8_SCHED;
;             PG8_LDA(At, 0, 1); PG8_STAGE(PG8_SB(0, 0), b2, voffB); PG8_STAGE(PG8_SB(0, 1), b2 + hstep, voffB); PG8_STAGE(PG8_SA(0, 0), a2, voffA);
;             PG8_WAIT_V(8); PG8_WAIT_L(0); PG8_BAR; PG8_MMA(1, 0, At, B0); PG8_MMA(1, 1, At, B1); PG8_BAR; PG8_SCHED;
;             PG8_LDB(B0, 1, 0); PG8_LDB(B1, 1, 1); PG8_SCHED; PG8_LDA(At, 1, 0); PG8_STAGE(PG8_SA(0, 1), a2 + hstep, voffA);
;             PG8_WAIT_V(8); PG8_WAIT_L(0); PG8_BAR; PG8_MMA(0, 0, At, B0); PG8_MMA(0, 1, At, B1); PG8_BAR; PG8_SCHED;
	s_setprio 1
	s_waitcnt lgkmcnt(0)
	v_mfma_f32_16x16x32_bf16 v[166:169], v[0:3], v[90:93], 0
	v_mfma_f32_16x16x32_bf16 v[174:177], v[0:3], v[134:137], 0
	v_mfma_f32_16x16x32_bf16 v[182:185], v[0:3], v[142:145], 0
	v_mfma_f32_16x16x32_bf16 v[0:3], v[0:3], v[154:157], 0
	v_mfma_f32_16x16x32_bf16 v[166:169], v[4:7], v[130:133], v[166:169]
	v_mfma_f32_16x16x32_bf16 v[170:173], v[8:11], v[90:93], 0
	v_mfma_f32_16x16x32_bf16 v[174:177], v[4:7], v[138:141], v[174:177]
	v_mfma_f32_16x16x32_bf16 v[178:181], v[8:11], v[134:137], 0
	v_mfma_f32_16x16x32_bf16 v[182:185], v[4:7], v[150:153], v[182:185]
	v_mfma_f32_16x16x32_bf16 v[186:189], v[8:11], v[142:145], 0
	v_mfma_f32_16x16x32_bf16 v[0:3], v[4:7], v[158:161], v[0:3]
	v_mfma_f32_16x16x32_bf16 v[4:7], v[8:11], v[154:157], 0
	v_mfma_f32_16x16x32_bf16 v[170:173], v[12:15], v[130:133], v[170:173]
	v_mfma_f32_16x16x32_bf16 v[178:181], v[12:15], v[138:141], v[178:181]
	v_mfma_f32_16x16x32_bf16 v[186:189], v[12:15], v[150:153], v[186:189]
	v_mfma_f32_16x16x32_bf16 v[4:7], v[12:15], v[158:161], v[4:7]
	s_setprio 0
	s_setprio 1
	v_mfma_f32_16x16x32_bf16 v[8:11], v[16:19], v[90:93], 0
	v_mfma_f32_16x16x32_bf16 v[12:15], v[24:27], v[90:93], 0
	v_mfma_f32_16x16x32_bf16 v[8:11], v[20:23], v[130:133], v[8:11]
	v_mfma_f32_16x16x32_bf16 v[12:15], v[28:31], v[130:133], v[12:15]
	v_mfma_f32_16x16x32_bf16 v[90:93], v[16:19], v[134:137], 0
	v_mfma_f32_16x16x32_bf16 v[130:133], v[24:27], v[134:137], 0
	v_mfma_f32_16x16x32_bf16 v[134:137], v[16:19], v[142:145], 0
	v_mfma_f32_16x16x32_bf16 v[16:19], v[16:19], v[154:157], 0
	v_mfma_f32_16x16x32_bf16 v[90:93], v[20:23], v[138:141], v[90:93]
	v_mfma_f32_16x16x32_bf16 v[130:133], v[28:31], v[138:141], v[130:133]
	v_mfma_f32_16x16x32_bf16 v[134:137], v[20:23], v[150:153], v[134:137]
	v_mfma_f32_16x16x32_bf16 v[138:141], v[24:27], v[142:145], 0
	v_mfma_f32_16x16x32_bf16 v[16:19], v[20:23], v[158:161], v[16:19]
	v_mfma_f32_16x16x32_bf16 v[20:23], v[24:27], v[154:157], 0
	v_mfma_f32_16x16x32_bf16 v[138:141], v[28:31], v[150:153], v[138:141]
	v_mfma_f32_16x16x32_bf16 v[20:23], v[28:31], v[158:161], v[20:23]
	s_setprio 0
	s_barrier
	s_add_i32 s87, 0, 0x18000
	s_add_i32 s93, 0, 0x1c000
	v_add_u32_e32 v73, s87, v68
	v_add_u32_e32 v165, s93, v68
	ds_read_b128 v[24:27], v73
	ds_read_b128 v[28:31], v73 offset:1024
	ds_read_b128 v[142:145], v73 offset:2048
	ds_read_b128 v[150:153], v73 offset:3072
	ds_read_b128 v[154:157], v165
	ds_read_b128 v[158:161], v165 offset:1024
	ds_read_b128 v[190:193], v165 offset:2048
	ds_read_b128 v[194:197], v165 offset:3072
	s_add_u32 s88, s60, 0x10100
	s_addc_u32 s89, s61, 0
	s_mov_b32 m0, s73
	v_lshl_add_u64 v[236:237], s[88:89], 0, v[40:41]
	ds_read_b128 v[198:201], v72 offset:32768
	ds_read_b128 v[202:205], v72 offset:33792
	ds_read_b128 v[206:209], v72 offset:34816
	ds_read_b128 v[210:213], v72 offset:35840
	ds_read_b128 v[216:219], v72 offset:36864
	ds_read_b128 v[220:223], v72 offset:37888
	ds_read_b128 v[224:227], v72 offset:38912
	ds_read_b128 v[228:231], v72 offset:39936
	global_load_lds_dwordx4 v[236:237], off
	v_lshl_add_u64 v[236:237], s[88:89], 0, v[44:45]
	s_mov_b32 m0, s74
	s_nop 0
	global_load_lds_dwordx4 v[236:237], off
	s_waitcnt vmcnt(8)
	s_waitcnt lgkmcnt(0)
	s_barrier
	s_setprio 1
	s_waitcnt lgkmcnt(0)
	v_mfma_f32_16x16x32_bf16 v[94:97], v[24:27], v[198:201], v[94:97]
	v_mfma_f32_16x16x32_bf16 v[98:101], v[142:145], v[198:201], v[98:101]
	v_mfma_f32_16x16x32_bf16 v[102:105], v[24:27], v[206:209], v[102:105]
	v_mfma_f32_16x16x32_bf16 v[106:109], v[142:145], v[206:209], v[106:109]
	v_mfma_f32_16x16x32_bf16 v[110:113], v[24:27], v[216:219], v[110:113]
	v_mfma_f32_16x16x32_bf16 v[114:117], v[142:145], v[216:219], v[114:117]
	v_mfma_f32_16x16x32_bf16 v[118:121], v[24:27], v[224:227], v[118:121]
	v_mfma_f32_16x16x32_bf16 v[122:125], v[142:145], v[224:227], v[122:125]
	v_mfma_f32_16x16x32_bf16 v[94:97], v[28:31], v[202:205], v[94:97]
	v_mfma_f32_16x16x32_bf16 v[98:101], v[150:153], v[202:205], v[98:101]
	v_mfma_f32_16x16x32_bf16 v[102:105], v[28:31], v[210:213], v[102:105]
	v_mfma_f32_16x16x32_bf16 v[106:109], v[150:153], v[210:213], v[106:109]
	v_mfma_f32_16x16x32_bf16 v[110:113], v[28:31], v[220:223], v[110:113]
	v_mfma_f32_16x16x32_bf16 v[114:117], v[150:153], v[220:223], v[114:117]
	v_mfma_f32_16x16x32_bf16 v[118:121], v[28:31], v[228:231], v[118:121]
	v_mfma_f32_16x16x32_bf16 v[122:125], v[150:153], v[228:231], v[122:125]
	s_setprio 0
	s_setprio 1
	v_mfma_f32_16x16x32_bf16 v[126:129], v[154:157], v[198:201], v[126:129]
	v_mfma_f32_16x16x32_bf16 v[32:35], v[190:193], v[198:201], v[32:35]
	v_mfma_f32_16x16x32_bf16 v[36:39], v[154:157], v[206:209], v[36:39]
	v_mfma_f32_16x16x32_bf16 v[52:55], v[190:193], v[206:209], v[52:55]
	v_mfma_f32_16x16x32_bf16 v[74:77], v[154:157], v[216:219], v[74:77]
	v_mfma_f32_16x16x32_bf16 v[78:81], v[190:193], v[216:219], v[78:81]
	v_mfma_f32_16x16x32_bf16 v[82:85], v[154:157], v[224:227], v[82:85]
	v_mfma_f32_16x16x32_bf16 v[86:89], v[190:193], v[224:227], v[86:89]
	v_mfma_f32_16x16x32_bf16 v[126:129], v[158:161], v[202:205], v[126:129]
	v_mfma_f32_16x16x32_bf16 v[32:35], v[194:197], v[202:205], v[32:35]
	v_mfma_f32_16x16x32_bf16 v[36:39], v[158:161], v[210:213], v[36:39]
	v_mfma_f32_16x16x32_bf16 v[52:55], v[194:197], v[210:213], v[52:55]
	v_mfma_f32_16x16x32_bf16 v[74:77], v[158:161], v[220:223], v[74:77]
	v_mfma_f32_16x16x32_bf16 v[78:81], v[194:197], v[220:223], v[78:81]
	v_mfma_f32_16x16x32_bf16 v[82:85], v[158:161], v[228:231], v[82:85]
	v_mfma_f32_16x16x32_bf16 v[86:89], v[194:197], v[228:231], v[86:89]
	s_setprio 0
	s_barrier
; #define PG8_STAGE(bufoff, gbase, voff) do { _Pragma("unroll") for (int _i = 0; _i < 2; ++_i) \
;         __builtin_amdgcn_global_load_lds((const unsigned*)((const char*)(gbase) + (voff)[_i]), (LAS unsigned*)(lds + (bufoff) + ldsw + _i * 8192), 16, 0, 0); } while (0)
; #define PG8_LDA(dst, b, h) do { _Pragma("unroll") for (int m = 0; m < 4; ++m) _Pragma("unroll") for (int k = 0; k < 2; ++k) dst[m][k] = *(const LAS bf16x8*)(lds + PG8_SA(b, h) + aoff + m * 2048 + k * 1024); } while (0)
; #define PG8_LDB(dst, b, h) do { _Pragma("unroll") for (int n = 0; n < 2; ++n) _Pragma("unroll") for (int k = 0; k < 2; ++k) dst[n][k] = *(const LAS bf16x8*)(lds + PG8_SB(b, h) + boff + n * 2048 + k * 1024); } while (0)
; #define PG8_MMA(ai, bj, At, Bt) do { __builtin_amdgcn_s_setprio(1); _Pragma("unroll") for (int m = 0; m < 4; ++m) _Pragma("unroll") for (int n = 0; n < 2; ++n) _Pragma("unroll") for (int k = 0; k < 2; ++k) \
;         acc[ai][bj][m][n] = __builtin_amdgcn_mfma_f32_16x16x32_bf16(Bt[n][k], At[m][k], acc[ai][bj][m][n], 0, 0, 0); __builtin_amdgcn_s_setprio(0); } while (0)
; #define PG8_WAIT_V(n) asm volatile("s_waitcnt vmcnt(" #n ")" ::: "memory")
; #define PG8_WAIT_L(n) asm volatile("s_waitcnt lgkmcnt(" #n ")" ::: "memory")
; #define PG8_BAR __builtin_amdgcn_s_barrier()
; #define PG8_SCHED __builtin_amdgcn_sched_barrier(0)
; template <class Epi, bool ALIGN_EPI = false, bool SP2 = true>
; __device__ __forceinline__ void gemm_phase(LAS unsigned char* lds, const Gemm g, const StaticOrder& S, const Epi& E) {
;     ...
;             PG8_LDB(B0, 1, 0); PG8_LDB(B1, 1, 1); PG8_SCHED; PG8_LDA(At, 1, 0); PG8_STAGE(PG8_SA(0, 1), a2 + hstep, voffA);
;             PG8_WAIT_V(8); PG8_WAIT_L(0); PG8_BAR; PG8_MMA(0, 0, At, B0); PG8_MMA(0, 1, At, B1); PG8_BAR; PG8_SCHED;
;             PG8_LDA(At, 1, 1); PG8_STAGE(PG8_SB(1, 0), b3, voffB); PG8_STAGE(PG8_SB(1, 1), b3 + hstep, voffB); PG8_STAGE(PG8_SA(1, 0), a3, voffA);
;             PG8_WAIT_V(8); PG8_WAIT_L(0); PG8_BAR; PG8_MMA(1, 0, At, B0); PG8_MMA(1, 1, At, B1); PG8_BAR; PG8_SCHED;
	s_add_i32 s88, s87, s69
	s_add_i32 s87, s88, 0x2000
	v_lshl_add_u64 v[146:147], v[146:147], 0, s[18:19]
	s_mov_b32 m0, s88
	s_add_u32 s90, s62, 0x10180
	ds_read_b128 v[198:201], v72 offset:49152
	ds_read_b128 v[202:205], v72 offset:50176
	ds_read_b128 v[206:209], v72 offset:51200
	ds_read_b128 v[210:213], v72 offset:52224
	ds_read_b128 v[216:219], v72 offset:53248
	ds_read_b128 v[220:223], v72 offset:54272
	ds_read_b128 v[224:227], v72 offset:55296
	ds_read_b128 v[228:231], v72 offset:56320
	global_load_lds_dwordx4 v[146:147], off
	v_lshl_add_u64 v[146:147], v[162:163], 0, s[18:19]
	s_mov_b32 m0, s87
	s_addc_u32 s91, s63, 0
	s_add_i32 s62, s93, s69
	global_load_lds_dwordx4 v[146:147], off
	v_lshl_add_u64 v[146:147], s[90:91], 0, v[42:43]
	s_mov_b32 m0, s62
	s_add_i32 s63, s62, 0x2000
	global_load_lds_dwordx4 v[146:147], off
	v_lshl_add_u64 v[146:147], s[90:91], 0, v[46:47]
	s_mov_b32 m0, s63
	s_nop 0
	global_load_lds_dwordx4 v[146:147], off
	v_lshl_add_u64 v[146:147], v[232:233], 0, s[18:19]
	s_mov_b32 m0, s75
	s_nop 0
	global_load_lds_dwordx4 v[146:147], off
	v_lshl_add_u64 v[146:147], v[234:235], 0, s[18:19]
	s_mov_b32 m0, s76
	s_nop 0
	global_load_lds_dwordx4 v[146:147], off
	s_waitcnt vmcnt(8)
	s_waitcnt lgkmcnt(0)
	s_barrier
	s_setprio 1
	s_waitcnt lgkmcnt(0)
	v_mfma_f32_16x16x32_bf16 v[166:169], v[24:27], v[198:201], v[166:169]
	v_mfma_f32_16x16x32_bf16 v[170:173], v[142:145], v[198:201], v[170:173]
	v_mfma_f32_16x16x32_bf16 v[174:177], v[24:27], v[206:209], v[174:177]
	v_mfma_f32_16x16x32_bf16 v[178:181], v[142:145], v[206:209], v[178:181]
	v_mfma_f32_16x16x32_bf16 v[182:185], v[24:27], v[216:219], v[182:185]
	v_mfma_f32_16x16x32_bf16 v[186:189], v[142:145], v[216:219], v[186:189]
	v_mfma_f32_16x16x32_bf16 v[0:3], v[24:27], v[224:227], v[0:3]
	v_mfma_f32_16x16x32_bf16 v[4:7], v[142:145], v[224:227], v[4:7]
	v_mfma_f32_16x16x32_bf16 v[166:169], v[28:31], v[202:205], v[166:169]
	v_mfma_f32_16x16x32_bf16 v[170:173], v[150:153], v[202:205], v[170:173]
	v_mfma_f32_16x16x32_bf16 v[174:177], v[28:31], v[210:213], v[174:177]
	v_mfma_f32_16x16x32_bf16 v[178:181], v[150:153], v[210:213], v[178:181]
	v_mfma_f32_16x16x32_bf16 v[182:185], v[28:31], v[220:223], v[182:185]
	v_mfma_f32_16x16x32_bf16 v[186:189], v[150:153], v[220:223], v[186:189]
	v_mfma_f32_16x16x32_bf16 v[0:3], v[28:31], v[228:231], v[0:3]
	v_mfma_f32_16x16x32_bf16 v[4:7], v[150:153], v[228:231], v[4:7]
	s_setprio 0
	s_setprio 1
	v_mfma_f32_16x16x32_bf16 v[8:11], v[154:157], v[198:201], v[8:11]
	v_mfma_f32_16x16x32_bf16 v[12:15], v[190:193], v[198:201], v[12:15]
	v_mfma_f32_16x16x32_bf16 v[24:27], v[154:157], v[206:209], v[90:93]
	v_mfma_f32_16x16x32_bf16 v[28:31], v[190:193], v[206:209], v[130:133]
	v_mfma_f32_16x16x32_bf16 v[90:93], v[154:157], v[216:219], v[134:137]
	v_mfma_f32_16x16x32_bf16 v[130:133], v[190:193], v[216:219], v[138:141]
	v_mfma_f32_16x16x32_bf16 v[16:19], v[154:157], v[224:227], v[16:19]
	v_mfma_f32_16x16x32_bf16 v[20:23], v[190:193], v[224:227], v[20:23]
	v_mfma_f32_16x16x32_bf16 v[8:11], v[158:161], v[202:205], v[8:11]
	v_mfma_f32_16x16x32_bf16 v[12:15], v[194:197], v[202:205], v[12:15]
	v_mfma_f32_16x16x32_bf16 v[24:27], v[158:161], v[210:213], v[24:27]
	v_mfma_f32_16x16x32_bf16 v[28:31], v[194:197], v[210:213], v[28:31]
	v_mfma_f32_16x16x32_bf16 v[90:93], v[158:161], v[220:223], v[90:93]
	v_mfma_f32_16x16x32_bf16 v[130:133], v[194:197], v[220:223], v[130:133]
	v_mfma_f32_16x16x32_bf16 v[16:19], v[158:161], v[228:231], v[16:19]
	v_mfma_f32_16x16x32_bf16 v[20:23], v[194:197], v[228:231], v[20:23]
	s_setprio 0
	s_barrier
	ds_read_b128 v[134:137], v70
	ds_read_b128 v[138:141], v70 offset:1024
	ds_read_b128 v[142:145], v70 offset:2048
	ds_read_b128 v[150:153], v70 offset:3072
	ds_read_b128 v[154:157], v71
	ds_read_b128 v[158:161], v71 offset:1024
	ds_read_b128 v[190:193], v71 offset:2048
	ds_read_b128 v[194:197], v71 offset:3072
	s_add_u32 s60, s60, 0x10180
	s_addc_u32 s61, s61, 0
	s_mov_b32 m0, s81
	v_lshl_add_u64 v[146:147], s[60:61], 0, v[40:41]
	ds_read_b128 v[198:201], v72
	ds_read_b128 v[202:205], v72 offset:1024
	ds_read_b128 v[206:209], v72 offset:2048
	ds_read_b128 v[210:213], v72 offset:3072
	ds_read_b128 v[216:219], v72 offset:4096
	ds_read_b128 v[220:223], v72 offset:5120
	ds_read_b128 v[224:227], v72 offset:6144
	ds_read_b128 v[228:231], v72 offset:7168
	global_load_lds_dwordx4 v[146:147], off
	v_lshl_add_u64 v[146:147], s[60:61], 0, v[44:45]
	s_mov_b32 m0, s82
	s_nop 0
	global_load_lds_dwordx4 v[146:147], off
	s_waitcnt vmcnt(8)
	s_waitcnt lgkmcnt(0)
	s_barrier
; #define PG8_STAGE(bufoff, gbase, voff) do { _Pragma("unroll") for (int _i = 0; _i < 2; ++_i) \
;         __builtin_amdgcn_global_load_lds((const unsigned*)((const char*)(gbase) + (voff)[_i]), (LAS unsigned*)(lds + (bufoff) + ldsw + _i * 8192), 16, 0, 0); } while (0)
; #define PG8_LDA(dst, b, h) do { _Pragma("unroll") for (int m = 0; m < 4; ++m) _Pragma("unroll") for (int k = 0; k < 2; ++k) dst[m][k] = *(const LAS bf16x8*)(lds + PG8_SA(b, h) + aoff + m * 2048 + k * 1024); } while (0)
; #define PG8_LDB(dst, b, h) do { _Pragma("unroll") for (int n = 0; n < 2; ++n) _Pragma("unroll") for (int k = 0; k < 2; ++k) dst[n][k] = *(const LAS bf16x8*)(lds + PG8_SB(b, h) + boff + n * 2048 + k * 1024); } while (0)
; #define PG8_MMA(ai, bj, At, Bt) do { __builtin_amdgcn_s_setprio(1); _Pragma("unroll") for (int m = 0; m < 4; ++m) _Pragma("unroll") for (int n = 0; n < 2; ++n) _Pragma("unroll") for (int k = 0; k < 2; ++k) \
;         acc[ai][bj][m][n] = __builtin_amdgcn_mfma_f32_16x16x32_bf16(Bt[n][k], At[m][k], acc[ai][bj][m][n], 0, 0, 0); __builtin_amdgcn_s_setprio(0); } while (0)
; #define PG8_WAIT_V(n) asm volatile("s_waitcnt vmcnt(" #n ")" ::: "memory")
; #define PG8_WAIT_L(n) asm volatile("s_waitcnt lgkmcnt(" #n ")" ::: "memory")
; #define PG8_BAR __builtin_amdgcn_s_barrier()
; #define PG8_SCHED __builtin_amdgcn_sched_barrier(0)
; template <class Epi, bool ALIGN_EPI = false, bool SP2 = true>
; __device__ __forceinline__ void gemm_phase(LAS unsigned char* lds, const Gemm g, const StaticOrder& S, const Epi& E) {
;     ...
;             PG8_LDB(B0, 0, 0); PG8_LDB(B1, 0, 1); PG8_SCHED; PG8_LDA(At, 0, 0); PG8_STAGE(PG8_SA(1, 1), a1 + hstep, voffA);
;             PG8_WAIT_V(8); PG8_WAIT_L(0); PG8_BAR; PG8_MMA(0, 0, At, B0); PG8_MMA(0, 1, At, B1); PG8_BAR; PG8_SCHED;
;             PG8_LDA(At, 0, 1); PG8_STAGE(PG8_SB(0, 0), b2, voffB); PG8_STAGE(PG8_SB(0, 1), b2 + hstep, voffB); PG8_STAGE(PG8_SA(0, 0), a2, voffA);
;             PG8_WAIT_V(8); PG8_WAIT_L(0); PG8_BAR; PG8_MMA(1, 0, At, B0); PG8_MMA(1, 1, At, B1); PG8_BAR; PG8_SCHED;
	s_setprio 1
	s_waitcnt lgkmcnt(0)
	v_mfma_f32_16x16x32_bf16 v[94:97], v[134:137], v[198:201], v[94:97]
	v_mfma_f32_16x16x32_bf16 v[98:101], v[142:145], v[198:201], v[98:101]
	v_mfma_f32_16x16x32_bf16 v[102:105], v[134:137], v[206:209], v[102:105]
	v_mfma_f32_16x16x32_bf16 v[106:109], v[142:145], v[206:209], v[106:109]
	v_mfma_f32_16x16x32_bf16 v[110:113], v[134:137], v[216:219], v[110:113]
	v_mfma_f32_16x16x32_bf16 v[114:117], v[142:145], v[216:219], v[114:117]
	v_mfma_f32_16x16x32_bf16 v[118:121], v[134:137], v[224:227], v[118:121]
	v_mfma_f32_16x16x32_bf16 v[122:125], v[142:145], v[224:227], v[122:125]
	v_mfma_f32_16x16x32_bf16 v[94:97], v[138:141], v[202:205], v[94:97]
	v_mfma_f32_16x16x32_bf16 v[98:101], v[150:153], v[202:205], v[98:101]
	v_mfma_f32_16x16x32_bf16 v[102:105], v[138:141], v[210:213], v[102:105]
	v_mfma_f32_16x16x32_bf16 v[106:109], v[150:153], v[210:213], v[106:109]
	v_mfma_f32_16x16x32_bf16 v[110:113], v[138:141], v[220:223], v[110:113]
	v_mfma_f32_16x16x32_bf16 v[114:117], v[150:153], v[220:223], v[114:117]
	v_mfma_f32_16x16x32_bf16 v[118:121], v[138:141], v[228:231], v[118:121]
	v_mfma_f32_16x16x32_bf16 v[122:125], v[150:153], v[228:231], v[122:125]
	s_setprio 0
	s_setprio 1
	v_mfma_f32_16x16x32_bf16 v[126:129], v[154:157], v[198:201], v[126:129]
	v_mfma_f32_16x16x32_bf16 v[32:35], v[190:193], v[198:201], v[32:35]
	v_mfma_f32_16x16x32_bf16 v[36:39], v[154:157], v[206:209], v[36:39]
	v_mfma_f32_16x16x32_bf16 v[52:55], v[190:193], v[206:209], v[52:55]
	v_mfma_f32_16x16x32_bf16 v[74:77], v[154:157], v[216:219], v[74:77]
	v_mfma_f32_16x16x32_bf16 v[78:81], v[190:193], v[216:219], v[78:81]
	v_mfma_f32_16x16x32_bf16 v[82:85], v[154:157], v[224:227], v[82:85]
	v_mfma_f32_16x16x32_bf16 v[86:89], v[190:193], v[224:227], v[86:89]
	v_mfma_f32_16x16x32_bf16 v[126:129], v[158:161], v[202:205], v[126:129]
	v_mfma_f32_16x16x32_bf16 v[32:35], v[194:197], v[202:205], v[32:35]
	v_mfma_f32_16x16x32_bf16 v[36:39], v[158:161], v[210:213], v[36:39]
	v_mfma_f32_16x16x32_bf16 v[52:55], v[194:197], v[210:213], v[52:55]
	v_mfma_f32_16x16x32_bf16 v[74:77], v[158:161], v[220:223], v[74:77]
	v_mfma_f32_16x16x32_bf16 v[78:81], v[194:197], v[220:223], v[78:81]
	v_mfma_f32_16x16x32_bf16 v[82:85], v[158:161], v[228:231], v[82:85]
	v_mfma_f32_16x16x32_bf16 v[86:89], v[194:197], v[228:231], v[86:89]
	s_setprio 0
	s_barrier
	s_mov_b32 m0, s83
	v_lshl_add_u64 v[146:147], s[64:65], 0, v[42:43]
	s_add_u32 s60, s64, 0x10000
	ds_read_b128 v[198:201], v72 offset:16384
	ds_read_b128 v[202:205], v72 offset:17408
	ds_read_b128 v[206:209], v72 offset:18432
	ds_read_b128 v[210:213], v72 offset:19456
	ds_read_b128 v[216:219], v72 offset:20480
	ds_read_b128 v[220:223], v72 offset:21504
	ds_read_b128 v[224:227], v72 offset:22528
	ds_read_b128 v[228:231], v72 offset:23552
	global_load_lds_dwordx4 v[146:147], off
	v_lshl_add_u64 v[162:163], s[64:65], 0, v[46:47]
	s_mov_b32 m0, s25
	s_addc_u32 s61, s65, 0
	global_load_lds_dwordx4 v[162:163], off
	v_lshl_add_u64 v[232:233], s[60:61], 0, v[42:43]
	s_mov_b32 m0, s85
	v_lshl_add_u64 v[244:245], s[66:67], 0, v[40:41]
	global_load_lds_dwordx4 v[232:233], off
	v_lshl_add_u64 v[232:233], s[60:61], 0, v[46:47]
	s_mov_b32 m0, s86
	v_lshl_add_u64 v[246:247], s[66:67], 0, v[44:45]
	global_load_lds_dwordx4 v[232:233], off
	s_mov_b32 m0, s37
	s_nop 0
	global_load_lds_dwordx4 v[244:245], off
	s_mov_b32 m0, s72
	s_nop 0
	global_load_lds_dwordx4 v[246:247], off
	s_waitcnt vmcnt(8)
	s_waitcnt lgkmcnt(0)
	s_barrier
	s_setprio 1
	s_waitcnt lgkmcnt(0)
	v_mfma_f32_16x16x32_bf16 v[166:169], v[134:137], v[198:201], v[166:169]
	v_mfma_f32_16x16x32_bf16 v[170:173], v[142:145], v[198:201], v[170:173]
	v_mfma_f32_16x16x32_bf16 v[174:177], v[134:137], v[206:209], v[174:177]
	v_mfma_f32_16x16x32_bf16 v[178:181], v[142:145], v[206:209], v[178:181]
	v_mfma_f32_16x16x32_bf16 v[182:185], v[134:137], v[216:219], v[182:185]
	v_mfma_f32_16x16x32_bf16 v[186:189], v[142:145], v[216:219], v[186:189]
	v_mfma_f32_16x16x32_bf16 v[0:3], v[134:137], v[224:227], v[0:3]
	v_mfma_f32_16x16x32_bf16 v[4:7], v[142:145], v[224:227], v[4:7]
	v_mfma_f32_16x16x32_bf16 v[166:169], v[138:141], v[202:205], v[166:169]
	v_mfma_f32_16x16x32_bf16 v[170:173], v[150:153], v[202:205], v[170:173]
	v_mfma_f32_16x16x32_bf16 v[174:177], v[138:141], v[210:213], v[174:177]
	v_mfma_f32_16x16x32_bf16 v[178:181], v[150:153], v[210:213], v[178:181]
	v_mfma_f32_16x16x32_bf16 v[182:185], v[138:141], v[220:223], v[182:185]
	v_mfma_f32_16x16x32_bf16 v[186:189], v[150:153], v[220:223], v[186:189]
	v_mfma_f32_16x16x32_bf16 v[0:3], v[138:141], v[228:231], v[0:3]
	v_mfma_f32_16x16x32_bf16 v[4:7], v[150:153], v[228:231], v[4:7]
	s_setprio 0
	s_setprio 1
	v_mfma_f32_16x16x32_bf16 v[8:11], v[154:157], v[198:201], v[8:11]
	v_mfma_f32_16x16x32_bf16 v[134:137], v[158:161], v[202:205], v[8:11]
	v_mfma_f32_16x16x32_bf16 v[8:11], v[190:193], v[198:201], v[12:15]
	v_mfma_f32_16x16x32_bf16 v[12:15], v[194:197], v[202:205], v[8:11]
	v_mfma_f32_16x16x32_bf16 v[8:11], v[154:157], v[206:209], v[24:27]
	v_mfma_f32_16x16x32_bf16 v[138:141], v[158:161], v[210:213], v[8:11]
	v_mfma_f32_16x16x32_bf16 v[8:11], v[190:193], v[206:209], v[28:31]
	v_mfma_f32_16x16x32_bf16 v[28:31], v[194:197], v[210:213], v[8:11]
	v_mfma_f32_16x16x32_bf16 v[8:11], v[154:157], v[216:219], v[90:93]
	v_mfma_f32_16x16x32_bf16 v[90:93], v[158:161], v[220:223], v[8:11]
	v_mfma_f32_16x16x32_bf16 v[8:11], v[190:193], v[216:219], v[130:133]
	v_mfma_f32_16x16x32_bf16 v[130:133], v[194:197], v[220:223], v[8:11]
	v_mfma_f32_16x16x32_bf16 v[8:11], v[154:157], v[224:227], v[16:19]
	v_mfma_f32_16x16x32_bf16 v[142:145], v[158:161], v[228:231], v[8:11]
	v_mfma_f32_16x16x32_bf16 v[8:11], v[190:193], v[224:227], v[20:23]
	v_mfma_f32_16x16x32_bf16 v[150:153], v[194:197], v[228:231], v[8:11]
	s_setprio 0
	s_barrier
; #define PG8_STAGE(bufoff, gbase, voff) do { _Pragma("unroll") for (int _i = 0; _i < 2; ++_i) \
;         __builtin_amdgcn_global_load_lds((const unsigned*)((const char*)(gbase) + (voff)[_i]), (LAS unsigned*)(lds + (bufoff) + ldsw + _i * 8192), 16, 0, 0); } while (0)
; #define PG8_LDA(dst, b, h) do { _Pragma("unroll") for (int m = 0; m < 4; ++m) _Pragma("unroll") for (int k = 0; k < 2; ++k) dst[m][k] = *(const LAS bf16x8*)(lds + PG8_SA(b, h) + aoff + m * 2048 + k * 1024); } while (0)
; #define PG8_LDB(dst, b, h) do { _Pragma("unroll") for (int n = 0; n < 2; ++n) _Pragma("unroll") for (int k = 0; k < 2; ++k) dst[n][k] = *(const LAS bf16x8*)(lds + PG8_SB(b, h) + boff + n * 2048 + k * 1024); } while (0)
; #define PG8_MMA(ai, bj, At, Bt) do { __builtin_amdgcn_s_setprio(1); _Pragma("unroll") for (int m = 0; m < 4; ++m) _Pragma("unroll") for (int n = 0; n < 2; ++n) _Pragma("unroll") for (int k = 0; k < 2; ++k) \
;         acc[ai][bj][m][n] = __builtin_amdgcn_mfma_f32_16x16x32_bf16(Bt[n][k], At[m][k], acc[ai][bj][m][n], 0, 0, 0); __builtin_amdgcn_s_setprio(0); } while (0)
; #define PG8_WAIT_V(n) asm volatile("s_waitcnt vmcnt(" #n ")" ::: "memory")
; #define PG8_WAIT_L(n) asm volatile("s_waitcnt lgkmcnt(" #n ")" ::: "memory")
; #define PG8_BAR __builtin_amdgcn_s_barrier()
; #define PG8_SCHED __builtin_amdgcn_sched_barrier(0)
; template <class Epi, bool ALIGN_EPI = false, bool SP2 = true>
; __device__ __forceinline__ void gemm_phase(LAS unsigned char* lds, const Gemm g, const StaticOrder& S, const Epi& E) {
;     ...
;             PG8_LDB(B0, 1, 0); PG8_LDB(B1, 1, 1); PG8_SCHED; PG8_LDA(At, 1, 0); PG8_STAGE(PG8_SA(0, 1), a2 + hstep, voffA);
;             PG8_WAIT_V(8); PG8_WAIT_L(0); PG8_BAR; PG8_MMA(0, 0, At, B0); PG8_MMA(0, 1, At, B1); PG8_BAR; PG8_SCHED;
;             PG8_LDA(At, 1, 1); PG8_STAGE(PG8_SB(1, 0), b3, voffB); PG8_STAGE(PG8_SB(1, 1), b3 + hstep, voffB); PG8_STAGE(PG8_SA(1, 0), a3, voffA);
;             PG8_WAIT_V(8); PG8_WAIT_L(0); PG8_BAR; PG8_MMA(1, 0, At, B0); PG8_MMA(1, 1, At, B1); PG8_BAR; PG8_SCHED;
	s_nop 4
	ds_read_b128 v[8:11], v73
	ds_read_b128 v[20:23], v73 offset:1024
	ds_read_b128 v[154:157], v73 offset:2048
	ds_read_b128 v[158:161], v73 offset:3072
	ds_read_b128 v[190:193], v165
	ds_read_b128 v[194:197], v165 offset:1024
	ds_read_b128 v[198:201], v165 offset:2048
	ds_read_b128 v[202:205], v165 offset:3072
	s_add_u32 s60, s66, 0x10000
	s_addc_u32 s61, s67, 0
	s_mov_b32 m0, s73
	v_lshl_add_u64 v[232:233], s[60:61], 0, v[40:41]
	ds_read_b128 v[16:19], v72 offset:32768
	ds_read_b128 v[24:27], v72 offset:33792
	ds_read_b128 v[206:209], v72 offset:34816
	ds_read_b128 v[210:213], v72 offset:35840
	ds_read_b128 v[216:219], v72 offset:36864
	ds_read_b128 v[220:223], v72 offset:37888
	ds_read_b128 v[224:227], v72 offset:38912
	ds_read_b128 v[228:231], v72 offset:39936
	global_load_lds_dwordx4 v[232:233], off
	v_lshl_add_u64 v[232:233], s[60:61], 0, v[44:45]
	s_mov_b32 m0, s74
	s_nop 0
	global_load_lds_dwordx4 v[232:233], off
	s_waitcnt vmcnt(8)
	s_waitcnt lgkmcnt(0)
	s_barrier
	s_setprio 1
	s_waitcnt lgkmcnt(0)
	v_mfma_f32_16x16x32_bf16 v[94:97], v[8:11], v[16:19], v[94:97]
	v_mfma_f32_16x16x32_bf16 v[98:101], v[154:157], v[16:19], v[98:101]
	v_mfma_f32_16x16x32_bf16 v[102:105], v[8:11], v[206:209], v[102:105]
	v_mfma_f32_16x16x32_bf16 v[106:109], v[154:157], v[206:209], v[106:109]
	v_mfma_f32_16x16x32_bf16 v[110:113], v[8:11], v[216:219], v[110:113]
	v_mfma_f32_16x16x32_bf16 v[114:117], v[154:157], v[216:219], v[114:117]
	v_mfma_f32_16x16x32_bf16 v[118:121], v[8:11], v[224:227], v[118:121]
	v_mfma_f32_16x16x32_bf16 v[122:125], v[154:157], v[224:227], v[122:125]
	v_mfma_f32_16x16x32_bf16 v[94:97], v[20:23], v[24:27], v[94:97]
	v_mfma_f32_16x16x32_bf16 v[98:101], v[158:161], v[24:27], v[98:101]
	v_mfma_f32_16x16x32_bf16 v[102:105], v[20:23], v[210:213], v[102:105]
	v_mfma_f32_16x16x32_bf16 v[106:109], v[158:161], v[210:213], v[106:109]
	v_mfma_f32_16x16x32_bf16 v[110:113], v[20:23], v[220:223], v[110:113]
	v_mfma_f32_16x16x32_bf16 v[114:117], v[158:161], v[220:223], v[114:117]
	v_mfma_f32_16x16x32_bf16 v[118:121], v[20:23], v[228:231], v[118:121]
	v_mfma_f32_16x16x32_bf16 v[122:125], v[158:161], v[228:231], v[122:125]
	s_setprio 0
	s_setprio 1
	v_mfma_f32_16x16x32_bf16 v[126:129], v[190:193], v[16:19], v[126:129]
	v_mfma_f32_16x16x32_bf16 v[16:19], v[198:201], v[16:19], v[32:35]
	v_mfma_f32_16x16x32_bf16 v[232:235], v[202:205], v[24:27], v[16:19]
	v_mfma_f32_16x16x32_bf16 v[16:19], v[190:193], v[206:209], v[36:39]
	v_mfma_f32_16x16x32_bf16 v[236:239], v[194:197], v[210:213], v[16:19]
	v_mfma_f32_16x16x32_bf16 v[16:19], v[198:201], v[206:209], v[52:55]
	v_mfma_f32_16x16x32_bf16 v[206:209], v[202:205], v[210:213], v[16:19]
	v_mfma_f32_16x16x32_bf16 v[16:19], v[190:193], v[216:219], v[74:77]
	v_mfma_f32_16x16x32_bf16 v[74:77], v[194:197], v[220:223], v[16:19]
	v_mfma_f32_16x16x32_bf16 v[16:19], v[198:201], v[216:219], v[78:81]
	v_mfma_f32_16x16x32_bf16 v[78:81], v[202:205], v[220:223], v[16:19]
	v_mfma_f32_16x16x32_bf16 v[16:19], v[190:193], v[224:227], v[82:85]
	v_mfma_f32_16x16x32_bf16 v[82:85], v[194:197], v[228:231], v[16:19]
	v_mfma_f32_16x16x32_bf16 v[16:19], v[198:201], v[224:227], v[86:89]
	v_mfma_f32_16x16x32_bf16 v[126:129], v[194:197], v[24:27], v[126:129]
	v_mfma_f32_16x16x32_bf16 v[86:89], v[202:205], v[228:231], v[16:19]
	s_setprio 0
	s_barrier
	s_mov_b32 m0, s88
	s_nop 2
	v_lshl_add_u64 v[16:17], v[146:147], 0, s[0:1]
	s_add_u32 s60, s64, 0x10080
	ds_read_b128 v[36:39], v72 offset:49152
	ds_read_b128 v[52:55], v72 offset:50176
	ds_read_b128 v[210:213], v72 offset:51200
	ds_read_b128 v[216:219], v72 offset:52224
	ds_read_b128 v[220:223], v72 offset:53248
	ds_read_b128 v[224:227], v72 offset:54272
	ds_read_b128 v[228:231], v72 offset:55296
	ds_read_b128 v[240:243], v72 offset:56320
	global_load_lds_dwordx4 v[16:17], off
	v_lshl_add_u64 v[16:17], v[162:163], 0, s[0:1]
	s_mov_b32 m0, s87
	s_addc_u32 s61, s65, 0
	global_load_lds_dwordx4 v[16:17], off
	v_lshl_add_u64 v[16:17], s[60:61], 0, v[42:43]
	s_mov_b32 m0, s62
	s_nop 0
	global_load_lds_dwordx4 v[16:17], off
	v_lshl_add_u64 v[16:17], s[60:61], 0, v[46:47]
	s_mov_b32 m0, s63
	s_nop 0
	global_load_lds_dwordx4 v[16:17], off
	v_lshl_add_u64 v[16:17], v[244:245], 0, s[0:1]
	s_mov_b32 m0, s75
	s_nop 0
	global_load_lds_dwordx4 v[16:17], off
	v_lshl_add_u64 v[16:17], v[246:247], 0, s[0:1]
	s_mov_b32 m0, s76
	s_nop 0
	global_load_lds_dwordx4 v[16:17], off
	s_waitcnt vmcnt(8)
	s_waitcnt lgkmcnt(0)
	s_barrier
	s_setprio 1
	s_waitcnt lgkmcnt(0)
	v_mfma_f32_16x16x32_bf16 v[16:19], v[8:11], v[36:39], v[166:169]
	v_mfma_f32_16x16x32_bf16 v[166:169], v[20:23], v[52:55], v[16:19]
	v_mfma_f32_16x16x32_bf16 v[16:19], v[154:157], v[36:39], v[170:173]
	v_mfma_f32_16x16x32_bf16 v[170:173], v[158:161], v[52:55], v[16:19]
	v_mfma_f32_16x16x32_bf16 v[16:19], v[8:11], v[210:213], v[174:177]
	v_mfma_f32_16x16x32_bf16 v[174:177], v[20:23], v[216:219], v[16:19]
	v_mfma_f32_16x16x32_bf16 v[16:19], v[154:157], v[210:213], v[178:181]
	v_mfma_f32_16x16x32_bf16 v[32:35], v[158:161], v[216:219], v[16:19]
	v_mfma_f32_16x16x32_bf16 v[16:19], v[8:11], v[220:223], v[182:185]
	v_mfma_f32_16x16x32_bf16 v[0:3], v[8:11], v[228:231], v[0:3]
	v_mfma_f32_16x16x32_bf16 v[24:27], v[20:23], v[224:227], v[16:19]
	v_mfma_f32_16x16x32_bf16 v[16:19], v[154:157], v[220:223], v[186:189]
	v_mfma_f32_16x16x32_bf16 v[8:11], v[20:23], v[240:243], v[0:3]
	v_mfma_f32_16x16x32_bf16 v[0:3], v[154:157], v[228:231], v[4:7]
	v_mfma_f32_16x16x32_bf16 v[16:19], v[158:161], v[224:227], v[16:19]
	v_mfma_f32_16x16x32_bf16 v[0:3], v[158:161], v[240:243], v[0:3]
	s_setprio 0
	s_setprio 1
	v_mfma_f32_16x16x32_bf16 v[4:7], v[190:193], v[36:39], v[134:137]
	v_mfma_f32_16x16x32_bf16 v[134:137], v[194:197], v[52:55], v[4:7]
	v_mfma_f32_16x16x32_bf16 v[4:7], v[198:201], v[36:39], v[12:15]
	v_mfma_f32_16x16x32_bf16 v[154:157], v[202:205], v[52:55], v[4:7]
	v_mfma_f32_16x16x32_bf16 v[4:7], v[190:193], v[210:213], v[138:141]
	v_mfma_f32_16x16x32_bf16 v[138:141], v[194:197], v[216:219], v[4:7]
	v_mfma_f32_16x16x32_bf16 v[4:7], v[198:201], v[210:213], v[28:31]
	v_mfma_f32_16x16x32_bf16 v[36:39], v[202:205], v[216:219], v[4:7]
	v_mfma_f32_16x16x32_bf16 v[4:7], v[190:193], v[220:223], v[90:93]
	v_mfma_f32_16x16x32_bf16 v[28:31], v[194:197], v[224:227], v[4:7]
	v_mfma_f32_16x16x32_bf16 v[4:7], v[198:201], v[220:223], v[130:133]
	v_mfma_f32_16x16x32_bf16 v[20:23], v[202:205], v[224:227], v[4:7]
	v_mfma_f32_16x16x32_bf16 v[4:7], v[190:193], v[228:231], v[142:145]
	v_mfma_f32_16x16x32_bf16 v[12:15], v[194:197], v[240:243], v[4:7]
	v_mfma_f32_16x16x32_bf16 v[4:7], v[198:201], v[228:231], v[150:153]
	v_mfma_f32_16x16x32_bf16 v[4:7], v[202:205], v[240:243], v[4:7]
	s_setprio 0
	s_barrier
; __device__ __forceinline__ u32x4 pack8(const f32x4 a, const f32x4 b) { u32x4 w; w.x = cvt_pk_bf16(a[0], a[1]); w.y = cvt_pk_bf16(a[2], a[3]); w.z = cvt_pk_bf16(b[0], b[1]); w.w = cvt_pk_bf16(b[2], b[3]); return w; }
;     __device__ __forceinline__ void operator()(const Acc& acc, const Unit& u, int wr, int wc, int fr, int fq) const {
;         const int cb = u.pn * 256 + wc * 32 + 8 * fq;
;         bf16_t* Ob = O + (u.pm >= 32 ? delta2 - (long long)32 * 256 * DM : 0ll);
; #pragma unroll
;         for (int ai = 0; ai < 2; ++ai)
; #pragma unroll
;             for (int m = 0; m < 4; ++m) {
;                 const int row = u.pm * 256 + ai * 128 + wr * 64 + m * 16 + fr;
; #pragma unroll
;                 for (int bj = 0; bj < 2; ++bj) *(u32x4*)(Ob + (size_t)row * DM + cb + bj * 128) = pack8(acc[ai][bj][m][0], acc[ai][bj][m][1]);
;             }
;     }
	s_cmp_gt_i32 s36, 31
	s_cselect_b32 s25, 0x3800000, 0
	v_lshl_or_b32 v52, s84, 8, v69
	s_add_u32 s60, s8, s25
	v_lshl_add_u32 v54, s36, 8, v67
	s_addc_u32 s61, s9, 0
	v_ashrrev_i32_e32 v53, 31, v52
	v_ashrrev_i32_e32 v55, 31, v54
	v_lshl_add_u64 v[52:53], v[52:53], 1, s[60:61]
	v_lshlrev_b64 v[90:91], 12, v[54:55]
	v_lshl_add_u64 v[130:131], v[52:53], 0, v[90:91]
	v_cvt_pk_bf16_f32 v90, v94, v95
	v_cvt_pk_bf16_f32 v91, v96, v97
	v_cvt_pk_bf16_f32 v92, v98, v99
	v_cvt_pk_bf16_f32 v93, v100, v101
	global_store_dwordx4 v[130:131], v[90:93], off
	s_add_i32 s79, s79, s34
	s_andn2_b64 vcc, exec, s[4:5]
	v_cvt_pk_bf16_f32 v90, v126, v127
	v_cvt_pk_bf16_f32 v91, v128, v129
	v_cvt_pk_bf16_f32 v92, v232, v233
	v_cvt_pk_bf16_f32 v93, v234, v235
	global_store_dwordx4 v[130:131], v[90:93], off offset:256
	s_mov_b32 s84, s3
	s_mov_b32 s36, s24
	v_or_b32_e32 v90, 16, v54
	v_ashrrev_i32_e32 v91, 31, v90
	v_lshlrev_b64 v[90:91], 12, v[90:91]
	v_lshl_add_u64 v[94:95], v[52:53], 0, v[90:91]
	v_cvt_pk_bf16_f32 v90, v102, v103
	v_cvt_pk_bf16_f32 v91, v104, v105
	v_cvt_pk_bf16_f32 v92, v106, v107
	v_cvt_pk_bf16_f32 v93, v108, v109
	global_store_dwordx4 v[94:95], v[90:93], off
	s_mov_b64 s[62:63], s[28:29]
	s_mov_b64 s[60:61], s[26:27]
	v_cvt_pk_bf16_f32 v90, v236, v237
	v_cvt_pk_bf16_f32 v91, v238, v239
	v_cvt_pk_bf16_f32 v92, v206, v207
	v_cvt_pk_bf16_f32 v93, v208, v209
	global_store_dwordx4 v[94:95], v[90:93], off offset:256
	s_nop 1
	v_or_b32_e32 v90, 32, v54
	v_ashrrev_i32_e32 v91, 31, v90
	v_lshlrev_b64 v[90:91], 12, v[90:91]
	v_lshl_add_u64 v[94:95], v[52:53], 0, v[90:91]
	v_cvt_pk_bf16_f32 v90, v110, v111
	v_cvt_pk_bf16_f32 v91, v112, v113
	v_cvt_pk_bf16_f32 v92, v114, v115
	v_cvt_pk_bf16_f32 v93, v116, v117
	global_store_dwordx4 v[94:95], v[90:93], off
	v_cvt_pk_bf16_f32 v74, v74, v75
	v_cvt_pk_bf16_f32 v75, v76, v77
	v_cvt_pk_bf16_f32 v76, v78, v79
	v_cvt_pk_bf16_f32 v77, v80, v81
	global_store_dwordx4 v[94:95], v[74:77], off offset:256
	s_nop 1
	v_or_b32_e32 v74, 48, v54
	v_ashrrev_i32_e32 v75, 31, v74
	v_lshlrev_b64 v[74:75], 12, v[74:75]
	v_lshl_add_u64 v[78:79], v[52:53], 0, v[74:75]
	v_cvt_pk_bf16_f32 v74, v118, v119
	v_cvt_pk_bf16_f32 v75, v120, v121
	v_cvt_pk_bf16_f32 v76, v122, v123
	v_cvt_pk_bf16_f32 v77, v124, v125
	global_store_dwordx4 v[78:79], v[74:77], off
	s_nop 1
	v_cvt_pk_bf16_f32 v74, v82, v83
	v_cvt_pk_bf16_f32 v75, v84, v85
	v_cvt_pk_bf16_f32 v76, v86, v87
	v_cvt_pk_bf16_f32 v77, v88, v89
	global_store_dwordx4 v[78:79], v[74:77], off offset:256
	s_nop 1
	v_add_u32_e32 v74, 0x80, v54
	v_ashrrev_i32_e32 v75, 31, v74
	v_lshlrev_b64 v[74:75], 12, v[74:75]
	v_lshl_add_u64 v[78:79], v[52:53], 0, v[74:75]
	v_cvt_pk_bf16_f32 v74, v166, v167
	v_cvt_pk_bf16_f32 v75, v168, v169
	v_cvt_pk_bf16_f32 v76, v170, v171
	v_cvt_pk_bf16_f32 v77, v172, v173
	global_store_dwordx4 v[78:79], v[74:77], off
	s_nop 1
	v_cvt_pk_bf16_f32 v74, v134, v135
	v_cvt_pk_bf16_f32 v75, v136, v137
	v_cvt_pk_bf16_f32 v76, v154, v155
	v_cvt_pk_bf16_f32 v77, v156, v157
	global_store_dwordx4 v[78:79], v[74:77], off offset:256
	s_nop 1
	v_add_u32_e32 v74, 0x90, v54
	v_ashrrev_i32_e32 v75, 31, v74
	v_lshlrev_b64 v[74:75], 12, v[74:75]
	v_lshl_add_u64 v[78:79], v[52:53], 0, v[74:75]
	v_cvt_pk_bf16_f32 v74, v174, v175
	v_cvt_pk_bf16_f32 v75, v176, v177
	v_cvt_pk_bf16_f32 v76, v32, v33
	v_cvt_pk_bf16_f32 v77, v34, v35
	global_store_dwordx4 v[78:79], v[74:77], off
	v_cvt_pk_bf16_f32 v32, v138, v139
	v_cvt_pk_bf16_f32 v33, v140, v141
	v_cvt_pk_bf16_f32 v34, v36, v37
	v_cvt_pk_bf16_f32 v35, v38, v39
	global_store_dwordx4 v[78:79], v[32:35], off offset:256
	v_cvt_pk_bf16_f32 v24, v24, v25
	v_cvt_pk_bf16_f32 v25, v26, v27
	v_cvt_pk_bf16_f32 v26, v16, v17
	v_cvt_pk_bf16_f32 v27, v18, v19
	s_nop 1
	v_add_u32_e32 v32, 0xa0, v54
	v_ashrrev_i32_e32 v33, 31, v32
	v_lshlrev_b64 v[32:33], 12, v[32:33]
	v_lshl_add_u64 v[32:33], v[52:53], 0, v[32:33]
	global_store_dwordx4 v[32:33], v[24:27], off
	v_cvt_pk_bf16_f32 v16, v28, v29
	v_cvt_pk_bf16_f32 v17, v30, v31
	v_cvt_pk_bf16_f32 v18, v20, v21
	v_cvt_pk_bf16_f32 v19, v22, v23
	global_store_dwordx4 v[32:33], v[16:19], off offset:256
	v_cvt_pk_bf16_f32 v8, v8, v9
	v_cvt_pk_bf16_f32 v9, v10, v11
	v_cvt_pk_bf16_f32 v10, v0, v1
	v_cvt_pk_bf16_f32 v11, v2, v3
	s_nop 1
	v_add_u32_e32 v16, 0xb0, v54
	v_ashrrev_i32_e32 v17, 31, v16
	v_lshlrev_b64 v[16:17], 12, v[16:17]
	v_lshl_add_u64 v[16:17], v[52:53], 0, v[16:17]
	global_store_dwordx4 v[16:17], v[8:11], off
	v_cvt_pk_bf16_f32 v0, v12, v13
	v_cvt_pk_bf16_f32 v1, v14, v15
	v_cvt_pk_bf16_f32 v2, v4, v5
	v_cvt_pk_bf16_f32 v3, v6, v7
	global_store_dwordx4 v[16:17], v[0:3], off offset:256
	s_cbranch_vccz .LBB0_307

; __device__ __forceinline__ unsigned xb_ld(unsigned* p)              { return __hip_atomic_load(p, __ATOMIC_RELAXED, __HIP_MEMORY_SCOPE_AGENT); }
; __device__ __forceinline__ unsigned xb_add(unsigned* p, unsigned v) { return __hip_atomic_fetch_add(p, v, __ATOMIC_RELAXED, __HIP_MEMORY_SCOPE_AGENT); }
; #define XB_SPIN(cond, bar) do { unsigned _sp = 0; while (cond) { __builtin_amdgcn_s_sleep(1); \
;     if ((++_sp & 255u) == 0u) { if (xb_ld(&(bar)[XB_TMO])) break; if (_sp > XB_SPIN_CAP) { atomicAdd(&(bar)[XB_TMO], 1u); break; } } } } while (0)
; __device__ __forceinline__ void xcd_barrier(const XcdBarrier& b) {
;     asm volatile("s_waitcnt vmcnt(0)" ::: "memory");
;     __syncthreads();
;     if (threadIdx.x == 0) {
;         unsigned* bar = b.bar;
;         __builtin_amdgcn_s_waitcnt(0);
;         unsigned nloc = b.st[0], nx = b.st[1];
;         if (nloc == 0u) { xcd_barrier_complete(bar, b.x, nloc, nx); b.st[0] = nloc; b.st[1] = nx; }
;         const unsigned old = xb_add(&bar[XB_XSUB(b.x)], 1u);
;         const unsigned gen = old / nloc;
;         if (old + 1u == (gen + 1u) * nloc) {
;             __builtin_amdgcn_fence(__ATOMIC_RELEASE, "agent");
;             asm volatile("s_waitcnt vmcnt(0)" ::: "memory");
;             const unsigned og = xb_add(&bar[XB_TOP], 1u);
;             const unsigned tg = og / nx;
;             if (og + 1u == (tg + 1u) * nx) xb_add(&bar[XB_TOPGEN], 1u);
;             else XB_SPIN(xb_ld(&bar[XB_TOPGEN]) == tg, bar);
;             __builtin_amdgcn_fence(__ATOMIC_ACQUIRE, "agent");
;             xb_add(&bar[XB_XGEN(b.x)], 1u);
;             asm volatile("s_waitcnt vmcnt(0)" ::: "memory");
;         } else {
;             XB_SPIN(xb_ld(&bar[XB_XGEN(b.x)]) == gen, bar);
;             __builtin_amdgcn_fence(__ATOMIC_ACQUIRE, "agent");
;             asm volatile("s_waitcnt vmcnt(0)" ::: "memory");
;         }
;     }
;     __syncthreads();
; }
.LBB0_366:
	s_cmp_gt_u32 s43, 4
	s_cselect_b64 s[0:1], -1, 0
	s_and_b64 s[0:1], s[16:17], s[0:1]
	s_andn2_b64 vcc, exec, s[0:1]
	s_cbranch_vccnz .LBB0_416
	s_waitcnt vmcnt(0)
	s_waitcnt vmcnt(0) lgkmcnt(0)
	s_barrier
	s_and_saveexec_b64 s[0:1], s[12:13]
	s_cbranch_execz .LBB0_415
	s_and_b32 s98, s2, 7
	s_lshl_b32 s98, s98, 2
	s_bfe_u32 s99, s2, 0x20003
	s_or_b32 s98, s98, s99
	s_lshl_b32 s98, s98, 6
	s_add_i32 s98, s98, 0xa400
	v_mov_b32_e32 v250, s98
	global_load_dword v251, v250, s[54:55] offset:8 sc1
	v_mov_b32_e32 v252, 1
	v_mov_b32_e32 v253, 0x2000c
	s_waitcnt vmcnt(0)
	v_readfirstlane_b32 s99, v251
	s_bcnt1_i32_b32 s99, s99
	v_mov_b32_e32 v254, s99
	ds_write_b32 v253, v254
	s_cmp_eq_u32 s99, 1
	s_cbranch_scc1 .Lpb3_fast
	buffer_wbl2 sc1
	s_waitcnt vmcnt(0)
.Lpb3_fast:
	global_atomic_add v250, v252, s[54:55]

; #define SEAM(k) do { if (IN(k) && hi > (k) + 1) xcd_barrier(xbar); } while (0)
; __global__ void __launch_bounds__(NTHREADS, 2) mk_fwd(Params P) {
;     ...
;     SEAM(3);
;     if (IN(5)) {
;         transpose_convert(lds, P.w_in_b, WINB, 2048, 8192, G, bid);
;         pg8::Gemm g{X1B, WG0, MTOK, 2048, 2048, 1 << 30, 0}; pg8::StaticOrder S; S.init(MTOK, 2048, G, bid);
;         EpiPle<false> E{X1B, PP0, SLOTA, nullptr}; pg8::gemm_phase<EpiPle<false>, true>(lds, g, S, E);
.LBB0_424:
	s_and_saveexec_b64 s[100:101], s[12:13]
	s_cbranch_execz .Lpw3_done
	s_and_b32 s98, s2, 7
	s_lshl_b32 s98, s98, 2
	s_bfe_u32 s99, s2, 0x20003
	s_or_b32 s98, s98, s99
	s_lshl_b32 s98, s98, 6
	s_add_i32 s98, s98, 0xa400
	v_mov_b32_e32 v250, s98
	s_mov_b32 s99, 0
.Lpw3_spin:
	global_load_dword v251, v250, s[54:55] sc1
	s_waitcnt vmcnt(0)
	v_readfirstlane_b32 s98, v251
	s_cmp_ge_u32 s98, 8
	s_cbranch_scc1 .Lpw3_ok
	s_sleep 1
	s_add_u32 s99, s99, 1
	s_cmp_lt_u32 s99, 0x40000
	s_cbranch_scc1 .Lpw3_spin
.Lpw3_ok:
	buffer_inv sc1
	s_waitcnt vmcnt(0)
.Lpw3_done:
	s_or_b64 exec, exec, s[100:101]
	s_cmpk_gt_i32 s2, 0xff
	v_readfirstlane_b32 s18, v164
	s_waitcnt vmcnt(0) lgkmcnt(0)
	s_barrier
	s_cbranch_scc1 .LBB0_448
	s_ashr_i32 s3, s2, 31
	s_lshr_b32 s4, s3, 29
	s_add_i32 s7, s2, s4
	s_and_b32 s4, s7, -8
	s_sub_i32 s16, s2, s4
	s_cmp_gt_i32 s16, -1
	s_cbranch_scc0 .LBB0_427
	s_lshl_b32 s6, s16, 5
	s_cbranch_execz .LBB0_428
	s_branch .LBB0_429

; __device__ __forceinline__ unsigned xb_ld(unsigned* p)              { return __hip_atomic_load(p, __ATOMIC_RELAXED, __HIP_MEMORY_SCOPE_AGENT); }
; __device__ __forceinline__ unsigned xb_add(unsigned* p, unsigned v) { return __hip_atomic_fetch_add(p, v, __ATOMIC_RELAXED, __HIP_MEMORY_SCOPE_AGENT); }
; #define XB_SPIN(cond, bar) do { unsigned _sp = 0; while (cond) { __builtin_amdgcn_s_sleep(1); \
;     if ((++_sp & 255u) == 0u) { if (xb_ld(&(bar)[XB_TMO])) break; if (_sp > XB_SPIN_CAP) { atomicAdd(&(bar)[XB_TMO], 1u); break; } } } } while (0)
; __device__ __forceinline__ void xcd_barrier(const XcdBarrier& b) {
;     asm volatile("s_waitcnt vmcnt(0)" ::: "memory");
;     __syncthreads();
;     if (threadIdx.x == 0) {
;         unsigned* bar = b.bar;
;         __builtin_amdgcn_s_waitcnt(0);
;         unsigned nloc = b.st[0], nx = b.st[1];
;         if (nloc == 0u) { xcd_barrier_complete(bar, b.x, nloc, nx); b.st[0] = nloc; b.st[1] = nx; }
;         const unsigned old = xb_add(&bar[XB_XSUB(b.x)], 1u);
;         const unsigned gen = old / nloc;
;         if (old + 1u == (gen + 1u) * nloc) {
;             __builtin_amdgcn_fence(__ATOMIC_RELEASE, "agent");
;             asm volatile("s_waitcnt vmcnt(0)" ::: "memory");
;             const unsigned og = xb_add(&bar[XB_TOP], 1u);
;             const unsigned tg = og / nx;
;             if (og + 1u == (tg + 1u) * nx) xb_add(&bar[XB_TOPGEN], 1u);
;             else XB_SPIN(xb_ld(&bar[XB_TOPGEN]) == tg, bar);
;             __builtin_amdgcn_fence(__ATOMIC_ACQUIRE, "agent");
;             xb_add(&bar[XB_XGEN(b.x)], 1u);
;             asm volatile("s_waitcnt vmcnt(0)" ::: "memory");
;         } else {
;             XB_SPIN(xb_ld(&bar[XB_XGEN(b.x)]) == gen, bar);
;             __builtin_amdgcn_fence(__ATOMIC_ACQUIRE, "agent");
;             asm volatile("s_waitcnt vmcnt(0)" ::: "memory");
;         }
;     }
;     __syncthreads();
; }
.LBB0_787:
	s_cmp_gt_u32 s43, 9
	s_cselect_b64 s[0:1], -1, 0
	s_and_b64 s[0:1], s[8:9], s[0:1]
	s_andn2_b64 vcc, exec, s[0:1]
	s_cbranch_vccnz .LBB0_837
	s_waitcnt vmcnt(0)
	s_waitcnt vmcnt(0) lgkmcnt(0)
	s_barrier
	s_and_saveexec_b64 s[0:1], s[12:13]
	s_cbranch_execz .LBB0_836
	s_and_b32 s98, s2, 7
	s_lshl_b32 s98, s98, 2
	s_bfe_u32 s99, s2, 0x20003
	s_or_b32 s98, s98, s99
	s_lshl_b32 s98, s98, 6
	s_add_i32 s98, s98, 0xa400
	v_mov_b32_e32 v250, s98
	v_mov_b32_e32 v252, 1
	v_mov_b32_e32 v253, 0x2000c
	ds_read_b32 v254, v253
	s_waitcnt lgkmcnt(0)
	v_readfirstlane_b32 s99, v254
	s_cmp_eq_u32 s99, 1
	s_cbranch_scc1 .Lpb8_fast
	buffer_wbl2 sc1
	s_waitcnt vmcnt(0)
.Lpb8_fast:
	global_atomic_add v250, v252, s[54:55] offset:4
	v_mov_b32_e32 v253, 0xa100
	global_atomic_add v253, v252, s[54:55]
	s_mov_b32 s99, 0
.Lpw8_spin:
	global_load_dword v251, v250, s[54:55] offset:4 sc1
	s_waitcnt vmcnt(0)
	v_readfirstlane_b32 s98, v251
	s_cmp_ge_u32 s98, 8
	s_cbranch_scc1 .Lpw8_ok
	s_sleep 1
	s_add_u32 s99, s99, 1
	s_cmp_lt_u32 s99, 0x40000
	s_cbranch_scc1 .Lpw8_spin

; __device__ __forceinline__ float bf_lo(unsigned w) { return __uint_as_float(w << 16); }
; __device__ __forceinline__ float bf_hi(unsigned w) { return __uint_as_float(w & 0xffff0000u); }
; __device__ __forceinline__ float fast_sigmoid(float v) { return __builtin_amdgcn_rcpf(1.0f + __builtin_amdgcn_exp2f(-1.4426950408889634f * v)); }
;     __device__ __forceinline__ void operator()(const Acc& acc, const Unit& u, int wr, int wc, int fr, int fq) const {
;     ...
;         for (int ai = 0; ai < 2; ++ai) {
;             const size_t o0 = (size_t)(u.pm * 256 + ai * 128 + wr * 64 + fr) * DM + cb;
;             u32x4 xw[4][2], pw[4][2];
; #pragma unroll
;             for (int m = 0; m < 4; ++m)
; #pragma unroll
;                 for (int bj = 0; bj < 2; ++bj) { const size_t o = o0 + (size_t)m * 16 * DM + bj * 128; xw[m][bj] = *(const u32x4*)(xin + o); pw[m][bj] = *(const u32x4*)(pp + o); }
; #pragma unroll
;             for (int m = 0; m < 4; ++m)
; #pragma unroll
;                 for (int bj = 0; bj < 2; ++bj) {
;                     const size_t o = o0 + (size_t)m * 16 * DM + bj * 128;
;                     const u32x4 x = xw[m][bj], p = pw[m][bj];
;                     const f32x4 a0 = acc[ai][bj][m][0], a1 = acc[ai][bj][m][1];
;                     f32x4 r0, r1;
;                     r0[0] = bf_lo(x.x) + fast_sigmoid(a0[0]) * bf_lo(p.x); r0[1] = bf_hi(x.x) + fast_sigmoid(a0[1]) * bf_hi(p.x);
;                     r0[2] = bf_lo(x.y) + fast_sigmoid(a0[2]) * bf_lo(p.y); r0[3] = bf_hi(x.y) + fast_sigmoid(a0[3]) * bf_hi(p.y);
;                     r1[0] = bf_lo(x.z) + fast_sigmoid(a1[0]) * bf_lo(p.z); r1[1] = bf_hi(x.z) + fast_sigmoid(a1[1]) * bf_hi(p.z);
;                     r1[2] = bf_lo(x.w) + fast_sigmoid(a1[2]) * bf_lo(p.w); r1[3] = bf_hi(x.w) + fast_sigmoid(a1[3]) * bf_hi(p.w);
;                     if constexpr (OUT_F32) { *(f32x4*)(outf + o) = r0; *(f32x4*)(outf + o + 4) = r1; }
.LBB0_858:
	v_mov_b32_e32 v251, 0x3d0a100
	global_load_dword v250, v251, s[40:41] sc1
	v_lshl_add_u32 v182, s42, 8, v184
	v_lshl_or_b32 v180, s63, 8, v186
	v_ashrrev_i32_e32 v183, 31, v182
	v_ashrrev_i32_e32 v181, 31, v180
	v_lshlrev_b64 v[128:129], 11, v[182:183]
	v_lshl_add_u64 v[218:219], v[128:129], 0, v[180:181]
	v_lshlrev_b64 v[128:129], 1, v[218:219]
	v_lshl_add_u64 v[130:131], s[52:53], 0, v[128:129]
	v_lshl_add_u64 v[132:133], s[6:7], 0, v[128:129]
	global_load_dwordx4 v[190:193], v[130:131], off
	global_load_dwordx4 v[194:197], v[132:133], off
	v_mul_f32_e32 v124, 0xbfb8aa3b, v124
	v_mul_f32_e32 v125, 0xbfb8aa3b, v125
	v_mul_f32_e32 v120, 0xbfb8aa3b, v120
	v_mul_f32_e32 v121, 0xbfb8aa3b, v121
	v_exp_f32_e32 v124, v124
	v_exp_f32_e32 v125, v125
	v_exp_f32_e32 v120, v120
	v_exp_f32_e32 v121, v121
	v_or_b32_e32 v128, 0x100, v128
	v_add_f32_e32 v134, 1.0, v124
	v_add_f32_e32 v135, 1.0, v125
	v_add_f32_e32 v138, 1.0, v120
	v_add_f32_e32 v139, 1.0, v121
	v_lshl_add_u64 v[120:121], s[52:53], 0, v[128:129]
	v_lshl_add_u64 v[124:125], s[6:7], 0, v[128:129]
	global_load_dwordx4 v[198:201], v[120:121], off
	global_load_dwordx4 v[202:205], v[124:125], off
	v_mul_f32_e32 v126, 0xbfb8aa3b, v126
	v_mul_f32_e32 v127, 0xbfb8aa3b, v127
	v_exp_f32_e32 v126, v126
	v_add_co_u32_e32 v120, vcc, s51, v130
	v_exp_f32_e32 v127, v127
	s_nop 0
	v_addc_co_u32_e32 v121, vcc, 0, v131, vcc
	v_add_co_u32_e32 v124, vcc, s51, v132
	v_add_f32_e32 v136, 1.0, v126
	s_nop 0
	v_addc_co_u32_e32 v125, vcc, 0, v133, vcc
	v_add_co_u32_e32 v126, vcc, s59, v130
	v_add_f32_e32 v137, 1.0, v127
	s_nop 0
	v_addc_co_u32_e32 v127, vcc, 0, v131, vcc
	v_add_co_u32_e32 v128, vcc, s59, v132
	v_rcp_f32_e32 v216, v134
	s_nop 0
	v_addc_co_u32_e32 v129, vcc, 0, v133, vcc
	v_add_co_u32_e32 v130, vcc, s60, v130
	v_rcp_f32_e32 v217, v135
	s_nop 0
	v_addc_co_u32_e32 v131, vcc, 0, v131, vcc
	v_add_co_u32_e32 v214, vcc, s60, v132
	v_rcp_f32_e32 v220, v136
	s_nop 0
	v_addc_co_u32_e32 v215, vcc, 0, v133, vcc
	v_rcp_f32_e32 v221, v137
	v_rcp_f32_e32 v222, v138
	v_rcp_f32_e32 v223, v139
	global_load_dwordx4 v[206:209], v[120:121], off
	global_load_dwordx4 v[160:163], v[120:121], off offset:256
	global_load_dwordx4 v[210:213], v[124:125], off
	global_load_dwordx4 v[156:159], v[124:125], off offset:256
	global_load_dwordx4 v[152:155], v[126:127], off
	global_load_dwordx4 v[144:147], v[126:127], off offset:256
	global_load_dwordx4 v[148:151], v[128:129], off
	global_load_dwordx4 v[140:143], v[128:129], off offset:256
	global_load_dwordx4 v[136:139], v[130:131], off
	s_nop 0
	global_load_dwordx4 v[128:131], v[130:131], off offset:256
	s_nop 0
	global_load_dwordx4 v[132:135], v[214:215], off
	global_load_dwordx4 v[124:127], v[214:215], off offset:256
	v_mul_f32_e32 v122, 0xbfb8aa3b, v122
	v_mul_f32_e32 v123, 0xbfb8aa3b, v123
	v_exp_f32_e32 v122, v122
	v_exp_f32_e32 v123, v123
	v_mul_f32_e32 v116, 0xbfb8aa3b, v116
	v_mul_f32_e32 v117, 0xbfb8aa3b, v117
	v_exp_f32_e32 v116, v116
	v_exp_f32_e32 v117, v117
	v_mul_f32_e32 v118, 0xbfb8aa3b, v118
	v_mul_f32_e32 v119, 0xbfb8aa3b, v119
	v_exp_f32_e32 v118, v118
	v_exp_f32_e32 v119, v119
	v_mul_f32_e32 v112, 0xbfb8aa3b, v112
	v_mul_f32_e32 v113, 0xbfb8aa3b, v113
	v_exp_f32_e32 v112, v112
	v_exp_f32_e32 v113, v113
	v_mul_f32_e32 v114, 0xbfb8aa3b, v114
	v_mul_f32_e32 v115, 0xbfb8aa3b, v115
	v_exp_f32_e32 v114, v114
	v_exp_f32_e32 v115, v115
	v_add_f32_e32 v116, 1.0, v116
	v_add_f32_e32 v117, 1.0, v117
	v_mul_f32_e32 v108, 0xbfb8aa3b, v108
	v_mul_f32_e32 v109, 0xbfb8aa3b, v109
	s_waitcnt vmcnt(0)
	s_mov_b32 s99, 0
.Lp10_gchk:
	v_readfirstlane_b32 s98, v250
	s_cmp_ge_u32 s98, 0x100
	s_cbranch_scc1 .Lp10_gok
	s_sleep 1
	s_add_u32 s99, s99, 1
	s_cmp_gt_u32 s99, 0x40000
	s_cbranch_scc1 .Lp10_gok
	global_load_dword v250, v251, s[40:41] sc1
	s_waitcnt vmcnt(0)
	s_branch .Lp10_gchk
.Lp10_gok:
	v_lshlrev_b32_e32 v120, 16, v190
	v_and_b32_e32 v121, 0xffff0000, v190
	v_lshlrev_b32_e32 v214, 16, v194
	v_and_b32_e32 v215, 0xffff0000, v194
	v_lshlrev_b32_e32 v190, 16, v191
	v_and_b32_e32 v191, 0xffff0000, v191
	v_lshlrev_b32_e32 v194, 16, v195
	v_and_b32_e32 v195, 0xffff0000, v195
	v_lshlrev_b32_e32 v224, 16, v192
	v_and_b32_e32 v225, 0xffff0000, v192
	v_pk_fma_f32 v[214:215], v[216:217], v[214:215], v[120:121]
	v_lshlrev_b32_e32 v120, 16, v196
	v_and_b32_e32 v121, 0xffff0000, v196
	v_pk_fma_f32 v[216:217], v[220:221], v[194:195], v[190:191]
	v_pk_fma_f32 v[190:191], v[222:223], v[120:121], v[224:225]
	v_add_f32_e32 v120, 1.0, v122
	v_add_f32_e32 v121, 1.0, v123
	v_rcp_f32_e32 v120, v120
	v_rcp_f32_e32 v121, v121
	v_rcp_f32_e32 v116, v116
	v_rcp_f32_e32 v117, v117
	v_add_f32_e32 v118, 1.0, v118
	v_add_f32_e32 v119, 1.0, v119
	v_exp_f32_e32 v108, v108
	v_exp_f32_e32 v109, v109
	v_mul_f32_e32 v110, 0xbfb8aa3b, v110
	v_mul_f32_e32 v111, 0xbfb8aa3b, v111
	v_lshlrev_b32_e32 v122, 16, v193
	v_and_b32_e32 v123, 0xffff0000, v193
	v_lshlrev_b32_e32 v192, 16, v197
	v_and_b32_e32 v193, 0xffff0000, v197
	v_rcp_f32_e32 v118, v118
	v_rcp_f32_e32 v119, v119
	v_add_f32_e32 v112, 1.0, v112
	v_add_f32_e32 v113, 1.0, v113
	v_exp_f32_e32 v110, v110
	v_exp_f32_e32 v111, v111
	v_mul_f32_e32 v104, 0xbfb8aa3b, v104
	v_mul_f32_e32 v105, 0xbfb8aa3b, v105
	v_pk_fma_f32 v[192:193], v[120:121], v[192:193], v[122:123]
	v_lshl_add_u64 v[120:121], v[218:219], 2, s[38:39]
	v_rcp_f32_e32 v112, v112
	v_rcp_f32_e32 v113, v113
	v_add_f32_e32 v114, 1.0, v114
	v_add_f32_e32 v115, 1.0, v115
	v_exp_f32_e32 v104, v104
	v_exp_f32_e32 v105, v105
	v_mul_f32_e32 v106, 0xbfb8aa3b, v106
	v_mul_f32_e32 v107, 0xbfb8aa3b, v107
	global_store_dwordx4 v[120:121], v[190:193], off offset:16
	v_lshlrev_b32_e32 v122, 16, v198
; __device__ __forceinline__ float bf_lo(unsigned w) { return __uint_as_float(w << 16); }
; __device__ __forceinline__ float bf_hi(unsigned w) { return __uint_as_float(w & 0xffff0000u); }
; __device__ __forceinline__ float fast_sigmoid(float v) { return __builtin_amdgcn_rcpf(1.0f + __builtin_amdgcn_exp2f(-1.4426950408889634f * v)); }
;     __device__ __forceinline__ void operator()(const Acc& acc, const Unit& u, int wr, int wc, int fr, int fq) const {
;     ...
;                     const f32x4 a0 = acc[ai][bj][m][0], a1 = acc[ai][bj][m][1];
;                     f32x4 r0, r1;
;                     r0[0] = bf_lo(x.x) + fast_sigmoid(a0[0]) * bf_lo(p.x); r0[1] = bf_hi(x.x) + fast_sigmoid(a0[1]) * bf_hi(p.x);
;                     r0[2] = bf_lo(x.y) + fast_sigmoid(a0[2]) * bf_lo(p.y); r0[3] = bf_hi(x.y) + fast_sigmoid(a0[3]) * bf_hi(p.y);
;                     r1[0] = bf_lo(x.z) + fast_sigmoid(a1[0]) * bf_lo(p.z); r1[1] = bf_hi(x.z) + fast_sigmoid(a1[1]) * bf_hi(p.z);
;                     r1[2] = bf_lo(x.w) + fast_sigmoid(a1[2]) * bf_lo(p.w); r1[3] = bf_hi(x.w) + fast_sigmoid(a1[3]) * bf_hi(p.w);
;                     if constexpr (OUT_F32) { *(f32x4*)(outf + o) = r0; *(f32x4*)(outf + o + 4) = r1; }
	v_and_b32_e32 v123, 0xffff0000, v198
	v_lshlrev_b32_e32 v190, 16, v202
	v_and_b32_e32 v191, 0xffff0000, v202
	v_rcp_f32_e32 v114, v114
	v_rcp_f32_e32 v115, v115
	v_exp_f32_e32 v106, v106
	v_exp_f32_e32 v107, v107
	v_pk_fma_f32 v[116:117], v[116:117], v[190:191], v[122:123]
	v_lshlrev_b32_e32 v122, 16, v199
	v_and_b32_e32 v123, 0xffff0000, v199
	v_lshlrev_b32_e32 v190, 16, v203
	v_and_b32_e32 v191, 0xffff0000, v203
	v_add_f32_e32 v108, 1.0, v108
	v_add_f32_e32 v109, 1.0, v109
	v_mul_f32_e32 v100, 0xbfb8aa3b, v100
	v_mul_f32_e32 v101, 0xbfb8aa3b, v101
	v_pk_fma_f32 v[118:119], v[118:119], v[190:191], v[122:123]
	v_lshlrev_b32_e32 v122, 16, v200
	v_and_b32_e32 v123, 0xffff0000, v200
	v_lshlrev_b32_e32 v190, 16, v204
	v_and_b32_e32 v191, 0xffff0000, v204
	v_rcp_f32_e32 v108, v108
	v_rcp_f32_e32 v109, v109
	v_add_f32_e32 v110, 1.0, v110
	v_add_f32_e32 v111, 1.0, v111
	v_exp_f32_e32 v100, v100
	v_exp_f32_e32 v101, v101
	v_mul_f32_e32 v102, 0xbfb8aa3b, v102
	v_mul_f32_e32 v103, 0xbfb8aa3b, v103
	v_pk_fma_f32 v[112:113], v[112:113], v[190:191], v[122:123]
	v_lshlrev_b32_e32 v122, 16, v201
	v_and_b32_e32 v123, 0xffff0000, v201
	v_lshlrev_b32_e32 v190, 16, v205
	v_and_b32_e32 v191, 0xffff0000, v205
	v_rcp_f32_e32 v110, v110
	v_rcp_f32_e32 v111, v111
	v_add_f32_e32 v104, 1.0, v104
	v_add_f32_e32 v105, 1.0, v105
	v_exp_f32_e32 v102, v102
	v_exp_f32_e32 v103, v103
	v_mul_f32_e32 v96, 0xbfb8aa3b, v96
	v_mul_f32_e32 v97, 0xbfb8aa3b, v97
	v_pk_fma_f32 v[114:115], v[114:115], v[190:191], v[122:123]
	v_rcp_f32_e32 v104, v104
	v_rcp_f32_e32 v105, v105
	v_add_f32_e32 v106, 1.0, v106
	v_add_f32_e32 v107, 1.0, v107
	v_exp_f32_e32 v96, v96
	v_exp_f32_e32 v97, v97
	v_mul_f32_e32 v98, 0xbfb8aa3b, v98
	v_mul_f32_e32 v99, 0xbfb8aa3b, v99
	global_store_dwordx4 v[120:121], v[112:115], off offset:528
	v_rcp_f32_e32 v106, v106
	v_rcp_f32_e32 v107, v107
	v_lshlrev_b32_e32 v112, 16, v206
	v_and_b32_e32 v113, 0xffff0000, v206
	v_lshlrev_b32_e32 v114, 16, v210
	v_and_b32_e32 v115, 0xffff0000, v210
	v_exp_f32_e32 v98, v98
	v_exp_f32_e32 v99, v99
	v_pk_fma_f32 v[108:109], v[108:109], v[114:115], v[112:113]
	v_lshlrev_b32_e32 v112, 16, v207
	v_and_b32_e32 v113, 0xffff0000, v207
	v_lshlrev_b32_e32 v114, 16, v211
	v_and_b32_e32 v115, 0xffff0000, v211
	v_add_f32_e32 v100, 1.0, v100
	v_add_f32_e32 v101, 1.0, v101
	v_mul_f32_e32 v92, 0xbfb8aa3b, v92
	v_mul_f32_e32 v93, 0xbfb8aa3b, v93
	v_pk_fma_f32 v[110:111], v[110:111], v[114:115], v[112:113]
	v_lshlrev_b32_e32 v112, 16, v208
	v_and_b32_e32 v113, 0xffff0000, v208
	v_lshlrev_b32_e32 v114, 16, v212
	v_and_b32_e32 v115, 0xffff0000, v212
	v_rcp_f32_e32 v100, v100
	v_rcp_f32_e32 v101, v101
	v_add_f32_e32 v102, 1.0, v102
	v_add_f32_e32 v103, 1.0, v103
	v_exp_f32_e32 v92, v92
	v_exp_f32_e32 v93, v93
	v_mul_f32_e32 v94, 0xbfb8aa3b, v94
	v_mul_f32_e32 v95, 0xbfb8aa3b, v95
	v_pk_fma_f32 v[104:105], v[104:105], v[114:115], v[112:113]
	v_lshlrev_b32_e32 v112, 16, v209
	v_and_b32_e32 v113, 0xffff0000, v209
	v_lshlrev_b32_e32 v114, 16, v213
	v_and_b32_e32 v115, 0xffff0000, v213
	v_rcp_f32_e32 v102, v102
	v_rcp_f32_e32 v103, v103
	v_add_f32_e32 v96, 1.0, v96
	v_add_f32_e32 v97, 1.0, v97
	v_exp_f32_e32 v94, v94
	v_exp_f32_e32 v95, v95
	v_mul_f32_e32 v88, 0xbfb8aa3b, v88
	v_mul_f32_e32 v89, 0xbfb8aa3b, v89
	v_pk_fma_f32 v[106:107], v[106:107], v[114:115], v[112:113]
	v_lshl_add_u64 v[112:113], v[120:121], 0, s[12:13]
	v_rcp_f32_e32 v96, v96
	v_rcp_f32_e32 v97, v97
	v_add_f32_e32 v98, 1.0, v98
	v_add_f32_e32 v99, 1.0, v99
	v_exp_f32_e32 v88, v88
	v_exp_f32_e32 v89, v89
	v_mul_f32_e32 v90, 0xbfb8aa3b, v90
	v_mul_f32_e32 v91, 0xbfb8aa3b, v91
	global_store_dwordx4 v[112:113], v[104:107], off offset:16
	v_rcp_f32_e32 v98, v98
	v_rcp_f32_e32 v99, v99
	v_lshlrev_b32_e32 v104, 16, v160
	v_and_b32_e32 v105, 0xffff0000, v160
	v_lshlrev_b32_e32 v106, 16, v156
	v_and_b32_e32 v107, 0xffff0000, v156
	v_exp_f32_e32 v90, v90
	v_exp_f32_e32 v91, v91
	v_pk_fma_f32 v[100:101], v[100:101], v[106:107], v[104:105]
	v_lshlrev_b32_e32 v104, 16, v161
	v_and_b32_e32 v105, 0xffff0000, v161
	v_lshlrev_b32_e32 v106, 16, v157
	v_and_b32_e32 v107, 0xffff0000, v157
	v_add_f32_e32 v92, 1.0, v92
	v_add_f32_e32 v93, 1.0, v93
	v_mul_f32_e32 v84, 0xbfb8aa3b, v84
	v_mul_f32_e32 v85, 0xbfb8aa3b, v85
	v_pk_fma_f32 v[102:103], v[102:103], v[106:107], v[104:105]
	v_lshlrev_b32_e32 v104, 16, v162
	v_and_b32_e32 v105, 0xffff0000, v162
	v_lshlrev_b32_e32 v106, 16, v158
	v_and_b32_e32 v107, 0xffff0000, v158
	v_rcp_f32_e32 v92, v92
	v_rcp_f32_e32 v93, v93
	v_add_f32_e32 v94, 1.0, v94
	v_add_f32_e32 v95, 1.0, v95
	v_exp_f32_e32 v84, v84
	v_exp_f32_e32 v85, v85
	v_mul_f32_e32 v86, 0xbfb8aa3b, v86
	v_mul_f32_e32 v87, 0xbfb8aa3b, v87
	v_pk_fma_f32 v[96:97], v[96:97], v[106:107], v[104:105]
	v_lshlrev_b32_e32 v104, 16, v163
	v_and_b32_e32 v105, 0xffff0000, v163
	v_lshlrev_b32_e32 v106, 16, v159
	v_and_b32_e32 v107, 0xffff0000, v159
	v_rcp_f32_e32 v94, v94
	v_rcp_f32_e32 v95, v95
	v_add_f32_e32 v88, 1.0, v88
	v_add_f32_e32 v89, 1.0, v89
	v_exp_f32_e32 v86, v86
	v_exp_f32_e32 v87, v87
	v_mul_f32_e32 v80, 0xbfb8aa3b, v80
	v_mul_f32_e32 v81, 0xbfb8aa3b, v81
	v_pk_fma_f32 v[98:99], v[98:99], v[106:107], v[104:105]
	v_lshl_add_u64 v[104:105], v[120:121], 0, s[14:15]
	v_rcp_f32_e32 v88, v88
	v_rcp_f32_e32 v89, v89
	v_add_f32_e32 v90, 1.0, v90
	v_add_f32_e32 v91, 1.0, v91
	v_exp_f32_e32 v80, v80
	v_exp_f32_e32 v81, v81
	v_mul_f32_e32 v82, 0xbfb8aa3b, v82
	v_mul_f32_e32 v83, 0xbfb8aa3b, v83
	global_store_dwordx4 v[104:105], v[96:99], off offset:16
	v_rcp_f32_e32 v90, v90
	v_rcp_f32_e32 v91, v91
	v_lshlrev_b32_e32 v96, 16, v152
	v_and_b32_e32 v97, 0xffff0000, v152
	v_lshlrev_b32_e32 v98, 16, v148
; __device__ __forceinline__ float bf_lo(unsigned w) { return __uint_as_float(w << 16); }
; __device__ __forceinline__ float bf_hi(unsigned w) { return __uint_as_float(w & 0xffff0000u); }
; __device__ __forceinline__ float fast_sigmoid(float v) { return __builtin_amdgcn_rcpf(1.0f + __builtin_amdgcn_exp2f(-1.4426950408889634f * v)); }
;     __device__ __forceinline__ void operator()(const Acc& acc, const Unit& u, int wr, int wc, int fr, int fq) const {
;     ...
;                     const f32x4 a0 = acc[ai][bj][m][0], a1 = acc[ai][bj][m][1];
;                     f32x4 r0, r1;
;                     r0[0] = bf_lo(x.x) + fast_sigmoid(a0[0]) * bf_lo(p.x); r0[1] = bf_hi(x.x) + fast_sigmoid(a0[1]) * bf_hi(p.x);
;                     r0[2] = bf_lo(x.y) + fast_sigmoid(a0[2]) * bf_lo(p.y); r0[3] = bf_hi(x.y) + fast_sigmoid(a0[3]) * bf_hi(p.y);
;                     r1[0] = bf_lo(x.z) + fast_sigmoid(a1[0]) * bf_lo(p.z); r1[1] = bf_hi(x.z) + fast_sigmoid(a1[1]) * bf_hi(p.z);
;                     r1[2] = bf_lo(x.w) + fast_sigmoid(a1[2]) * bf_lo(p.w); r1[3] = bf_hi(x.w) + fast_sigmoid(a1[3]) * bf_hi(p.w);
;                     if constexpr (OUT_F32) { *(f32x4*)(outf + o) = r0; *(f32x4*)(outf + o + 4) = r1; }
	v_and_b32_e32 v99, 0xffff0000, v148
	v_exp_f32_e32 v82, v82
	v_exp_f32_e32 v83, v83
	v_pk_fma_f32 v[92:93], v[92:93], v[98:99], v[96:97]
	v_lshlrev_b32_e32 v96, 16, v153
	v_and_b32_e32 v97, 0xffff0000, v153
	v_lshlrev_b32_e32 v98, 16, v149
	v_and_b32_e32 v99, 0xffff0000, v149
	v_add_f32_e32 v84, 1.0, v84
	v_add_f32_e32 v85, 1.0, v85
	v_mul_f32_e32 v76, 0xbfb8aa3b, v76
	v_mul_f32_e32 v77, 0xbfb8aa3b, v77
	v_pk_fma_f32 v[94:95], v[94:95], v[98:99], v[96:97]
	v_lshlrev_b32_e32 v96, 16, v154
	v_and_b32_e32 v97, 0xffff0000, v154
	v_lshlrev_b32_e32 v98, 16, v150
	v_and_b32_e32 v99, 0xffff0000, v150
	v_rcp_f32_e32 v84, v84
	v_rcp_f32_e32 v85, v85
	v_add_f32_e32 v86, 1.0, v86
	v_add_f32_e32 v87, 1.0, v87
	v_exp_f32_e32 v76, v76
	v_exp_f32_e32 v77, v77
	v_mul_f32_e32 v78, 0xbfb8aa3b, v78
	v_mul_f32_e32 v79, 0xbfb8aa3b, v79
	v_pk_fma_f32 v[88:89], v[88:89], v[98:99], v[96:97]
	v_lshlrev_b32_e32 v96, 16, v155
	v_and_b32_e32 v97, 0xffff0000, v155
	v_lshlrev_b32_e32 v98, 16, v151
	v_and_b32_e32 v99, 0xffff0000, v151
	v_rcp_f32_e32 v86, v86
	v_rcp_f32_e32 v87, v87
	v_add_f32_e32 v80, 1.0, v80
	v_add_f32_e32 v81, 1.0, v81
	v_exp_f32_e32 v78, v78
	v_exp_f32_e32 v79, v79
	v_mul_f32_e32 v72, 0xbfb8aa3b, v72
	v_mul_f32_e32 v73, 0xbfb8aa3b, v73
	v_pk_fma_f32 v[90:91], v[90:91], v[98:99], v[96:97]
	v_lshl_add_u64 v[96:97], v[120:121], 0, s[16:17]
	v_rcp_f32_e32 v80, v80
	v_rcp_f32_e32 v81, v81
	v_add_f32_e32 v82, 1.0, v82
	v_add_f32_e32 v83, 1.0, v83
	v_exp_f32_e32 v72, v72
	v_exp_f32_e32 v73, v73
	v_mul_f32_e32 v74, 0xbfb8aa3b, v74
	v_mul_f32_e32 v75, 0xbfb8aa3b, v75
	global_store_dwordx4 v[96:97], v[88:91], off offset:16
	v_rcp_f32_e32 v82, v82
	v_rcp_f32_e32 v83, v83
	v_lshlrev_b32_e32 v88, 16, v144
	v_and_b32_e32 v89, 0xffff0000, v144
	v_lshlrev_b32_e32 v90, 16, v140
	v_and_b32_e32 v91, 0xffff0000, v140
	v_exp_f32_e32 v74, v74
	v_exp_f32_e32 v75, v75
	v_pk_fma_f32 v[84:85], v[84:85], v[90:91], v[88:89]
	v_lshlrev_b32_e32 v88, 16, v145
	v_and_b32_e32 v89, 0xffff0000, v145
	v_lshlrev_b32_e32 v90, 16, v141
	v_and_b32_e32 v91, 0xffff0000, v141
	v_add_f32_e32 v76, 1.0, v76
	v_add_f32_e32 v77, 1.0, v77
	v_mul_f32_e32 v68, 0xbfb8aa3b, v68
	v_mul_f32_e32 v69, 0xbfb8aa3b, v69
	v_pk_fma_f32 v[86:87], v[86:87], v[90:91], v[88:89]
	v_lshlrev_b32_e32 v88, 16, v146
	v_and_b32_e32 v89, 0xffff0000, v146
	v_lshlrev_b32_e32 v90, 16, v142
	v_and_b32_e32 v91, 0xffff0000, v142
	v_rcp_f32_e32 v76, v76
	v_rcp_f32_e32 v77, v77
	v_add_f32_e32 v78, 1.0, v78
	v_add_f32_e32 v79, 1.0, v79
	v_exp_f32_e32 v68, v68
	v_exp_f32_e32 v69, v69
	v_mul_f32_e32 v70, 0xbfb8aa3b, v70
	v_mul_f32_e32 v71, 0xbfb8aa3b, v71
	v_pk_fma_f32 v[80:81], v[80:81], v[90:91], v[88:89]
	v_lshlrev_b32_e32 v88, 16, v147
	v_and_b32_e32 v89, 0xffff0000, v147
	v_lshlrev_b32_e32 v90, 16, v143
	v_and_b32_e32 v91, 0xffff0000, v143
	v_rcp_f32_e32 v78, v78
	v_rcp_f32_e32 v79, v79
	v_add_f32_e32 v72, 1.0, v72
	v_add_f32_e32 v73, 1.0, v73
	v_exp_f32_e32 v70, v70
	v_exp_f32_e32 v71, v71
	v_mul_f32_e32 v64, 0xbfb8aa3b, v64
	v_mul_f32_e32 v65, 0xbfb8aa3b, v65
	v_pk_fma_f32 v[82:83], v[82:83], v[90:91], v[88:89]
	v_lshl_add_u64 v[88:89], v[120:121], 0, s[18:19]
	v_rcp_f32_e32 v72, v72
	v_rcp_f32_e32 v73, v73
	v_add_f32_e32 v74, 1.0, v74
	v_add_f32_e32 v75, 1.0, v75
	v_exp_f32_e32 v64, v64
	v_exp_f32_e32 v65, v65
	v_mul_f32_e32 v66, 0xbfb8aa3b, v66
	v_mul_f32_e32 v67, 0xbfb8aa3b, v67
	global_store_dwordx4 v[88:89], v[80:83], off offset:16
	v_rcp_f32_e32 v74, v74
	v_rcp_f32_e32 v75, v75
	v_lshlrev_b32_e32 v80, 16, v136
	v_and_b32_e32 v81, 0xffff0000, v136
	v_lshlrev_b32_e32 v82, 16, v132
	v_and_b32_e32 v83, 0xffff0000, v132
	v_exp_f32_e32 v66, v66
	v_exp_f32_e32 v67, v67
	v_pk_fma_f32 v[76:77], v[76:77], v[82:83], v[80:81]
	v_lshlrev_b32_e32 v80, 16, v137
	v_and_b32_e32 v81, 0xffff0000, v137
	v_lshlrev_b32_e32 v82, 16, v133
	v_and_b32_e32 v83, 0xffff0000, v133
	v_add_f32_e32 v68, 1.0, v68
	v_add_f32_e32 v69, 1.0, v69
	v_pk_fma_f32 v[78:79], v[78:79], v[82:83], v[80:81]
	v_lshlrev_b32_e32 v80, 16, v138
	v_and_b32_e32 v81, 0xffff0000, v138
	v_lshlrev_b32_e32 v82, 16, v134
	v_and_b32_e32 v83, 0xffff0000, v134
	v_rcp_f32_e32 v68, v68
	v_rcp_f32_e32 v69, v69
	v_add_f32_e32 v70, 1.0, v70
	v_add_f32_e32 v71, 1.0, v71
	v_add_co_u32_e32 v114, vcc, s59, v120
	v_pk_fma_f32 v[72:73], v[72:73], v[82:83], v[80:81]
	v_lshlrev_b32_e32 v80, 16, v139
	v_and_b32_e32 v81, 0xffff0000, v139
	v_lshlrev_b32_e32 v82, 16, v135
	v_and_b32_e32 v83, 0xffff0000, v135
	v_rcp_f32_e32 v70, v70
	v_rcp_f32_e32 v71, v71
	v_add_f32_e32 v64, 1.0, v64
	v_add_f32_e32 v65, 1.0, v65
	v_addc_co_u32_e32 v115, vcc, 0, v121, vcc
	v_pk_fma_f32 v[74:75], v[74:75], v[82:83], v[80:81]
	v_lshl_add_u64 v[80:81], v[120:121], 0, s[20:21]
	v_rcp_f32_e32 v64, v64
	v_rcp_f32_e32 v65, v65
	v_add_f32_e32 v66, 1.0, v66
	v_add_f32_e32 v67, 1.0, v67
	v_add_co_u32_e32 v98, vcc, s61, v120
	global_store_dwordx4 v[80:81], v[72:75], off offset:16
	v_rcp_f32_e32 v66, v66
	v_rcp_f32_e32 v67, v67
	v_lshlrev_b32_e32 v72, 16, v128
	v_and_b32_e32 v73, 0xffff0000, v128
	v_lshlrev_b32_e32 v74, 16, v124
	v_and_b32_e32 v75, 0xffff0000, v124
	v_addc_co_u32_e32 v99, vcc, 0, v121, vcc
	v_pk_fma_f32 v[68:69], v[68:69], v[74:75], v[72:73]
	v_lshlrev_b32_e32 v72, 16, v129
	v_and_b32_e32 v73, 0xffff0000, v129
	v_lshlrev_b32_e32 v74, 16, v125
	v_and_b32_e32 v75, 0xffff0000, v125
	v_add_co_u32_e32 v82, vcc, s62, v120
	v_pk_fma_f32 v[70:71], v[70:71], v[74:75], v[72:73]
	v_lshlrev_b32_e32 v72, 16, v130
	v_and_b32_e32 v73, 0xffff0000, v130
	v_lshlrev_b32_e32 v74, 16, v126
	v_and_b32_e32 v75, 0xffff0000, v126
	v_addc_co_u32_e32 v83, vcc, 0, v121, vcc
	v_pk_fma_f32 v[64:65], v[64:65], v[74:75], v[72:73]
; __device__ __forceinline__ float bf_lo(unsigned w) { return __uint_as_float(w << 16); }
; __device__ __forceinline__ float bf_hi(unsigned w) { return __uint_as_float(w & 0xffff0000u); }
; __device__ __forceinline__ float fast_sigmoid(float v) { return __builtin_amdgcn_rcpf(1.0f + __builtin_amdgcn_exp2f(-1.4426950408889634f * v)); }
;     __device__ __forceinline__ void operator()(const Acc& acc, const Unit& u, int wr, int wc, int fr, int fq) const {
;     ...
;             for (int m = 0; m < 4; ++m)
; #pragma unroll
;                 for (int bj = 0; bj < 2; ++bj) { const size_t o = o0 + (size_t)m * 16 * DM + bj * 128; xw[m][bj] = *(const u32x4*)(xin + o); pw[m][bj] = *(const u32x4*)(pp + o); }
; #pragma unroll
;             for (int m = 0; m < 4; ++m)
; #pragma unroll
;                 for (int bj = 0; bj < 2; ++bj) {
;                     const size_t o = o0 + (size_t)m * 16 * DM + bj * 128;
;                     const u32x4 x = xw[m][bj], p = pw[m][bj];
;                     const f32x4 a0 = acc[ai][bj][m][0], a1 = acc[ai][bj][m][1];
;                     f32x4 r0, r1;
;                     r0[0] = bf_lo(x.x) + fast_sigmoid(a0[0]) * bf_lo(p.x); r0[1] = bf_hi(x.x) + fast_sigmoid(a0[1]) * bf_hi(p.x);
;                     r0[2] = bf_lo(x.y) + fast_sigmoid(a0[2]) * bf_lo(p.y); r0[3] = bf_hi(x.y) + fast_sigmoid(a0[3]) * bf_hi(p.y);
;                     r1[0] = bf_lo(x.z) + fast_sigmoid(a1[0]) * bf_lo(p.z); r1[1] = bf_hi(x.z) + fast_sigmoid(a1[1]) * bf_hi(p.z);
;                     r1[2] = bf_lo(x.w) + fast_sigmoid(a1[2]) * bf_lo(p.w); r1[3] = bf_hi(x.w) + fast_sigmoid(a1[3]) * bf_hi(p.w);
;                     if constexpr (OUT_F32) { *(f32x4*)(outf + o) = r0; *(f32x4*)(outf + o + 4) = r1; }
	v_lshlrev_b32_e32 v72, 16, v131
	v_and_b32_e32 v73, 0xffff0000, v131
	v_lshlrev_b32_e32 v74, 16, v127
	v_and_b32_e32 v75, 0xffff0000, v127
	global_store_dwordx4 v[120:121], v[214:217], off
	global_store_dwordx4 v[120:121], v[116:119], off offset:512
	global_store_dwordx4 v[114:115], v[108:111], off
	global_store_dwordx4 v[114:115], v[100:103], off offset:512
	global_store_dwordx4 v[98:99], v[92:95], off
	global_store_dwordx4 v[98:99], v[84:87], off offset:512
	global_store_dwordx4 v[82:83], v[76:79], off
	v_pk_fma_f32 v[66:67], v[66:67], v[74:75], v[72:73]
	v_lshl_add_u64 v[72:73], v[120:121], 0, s[24:25]
	global_store_dwordx4 v[82:83], v[68:71], off offset:512
	global_store_dwordx4 v[72:73], v[64:67], off offset:16
	v_mul_f32_e32 v62, 0xbfb8aa3b, v62
	v_mul_f32_e32 v63, 0xbfb8aa3b, v63
	v_add_u32_e32 v64, 0x80, v182
	v_ashrrev_i32_e32 v65, 31, v64
	v_lshlrev_b64 v[64:65], 11, v[64:65]
	v_lshl_add_u64 v[128:129], v[64:65], 0, v[180:181]
	v_lshlrev_b64 v[64:65], 1, v[128:129]
	v_lshl_add_u64 v[66:67], s[52:53], 0, v[64:65]
	v_lshl_add_u64 v[68:69], s[6:7], 0, v[64:65]
	global_load_dwordx4 v[112:115], v[66:67], off
	global_load_dwordx4 v[116:119], v[68:69], off
	v_or_b32_e32 v64, 0x100, v64
	v_lshl_add_u64 v[70:71], s[52:53], 0, v[64:65]
	v_lshl_add_u64 v[64:65], s[6:7], 0, v[64:65]
	global_load_dwordx4 v[120:123], v[70:71], off
	global_load_dwordx4 v[124:127], v[64:65], off
	v_add_co_u32_e32 v64, vcc, s51, v66
	v_exp_f32_e32 v62, v62
	s_nop 0
	v_addc_co_u32_e32 v65, vcc, 0, v67, vcc
	v_add_co_u32_e32 v70, vcc, s51, v68
	v_exp_f32_e32 v63, v63
	s_nop 0
	v_addc_co_u32_e32 v71, vcc, 0, v69, vcc
	global_load_dwordx4 v[104:107], v[64:65], off
	global_load_dwordx4 v[100:103], v[64:65], off offset:256
	global_load_dwordx4 v[108:111], v[70:71], off
	global_load_dwordx4 v[96:99], v[70:71], off offset:256
	v_add_co_u32_e32 v64, vcc, s59, v66
	v_mul_f32_e32 v56, 0xbfb8aa3b, v56
	s_nop 0
	v_addc_co_u32_e32 v65, vcc, 0, v67, vcc
	v_add_co_u32_e32 v70, vcc, s59, v68
	v_mul_f32_e32 v57, 0xbfb8aa3b, v57
	s_nop 0
	v_addc_co_u32_e32 v71, vcc, 0, v69, vcc
	global_load_dwordx4 v[88:91], v[64:65], off
	global_load_dwordx4 v[84:87], v[64:65], off offset:256
	global_load_dwordx4 v[92:95], v[70:71], off
	global_load_dwordx4 v[80:83], v[70:71], off offset:256
	v_add_co_u32_e32 v64, vcc, s60, v66
	v_exp_f32_e32 v56, v56
	s_nop 0
	v_addc_co_u32_e32 v65, vcc, 0, v67, vcc
	v_add_co_u32_e32 v68, vcc, s60, v68
	global_load_dwordx4 v[72:75], v[64:65], off
	s_nop 0
	global_load_dwordx4 v[64:67], v[64:65], off offset:256
	v_addc_co_u32_e32 v69, vcc, 0, v69, vcc
	global_load_dwordx4 v[76:79], v[68:69], off
	s_nop 0
	global_load_dwordx4 v[68:71], v[68:69], off offset:256
	v_exp_f32_e32 v57, v57
	v_add_f32_e32 v62, 1.0, v62
	v_add_f32_e32 v63, 1.0, v63
	v_mul_f32_e32 v60, 0xbfb8aa3b, v60
	v_mul_f32_e32 v61, 0xbfb8aa3b, v61
	v_rcp_f32_e32 v62, v62
	v_rcp_f32_e32 v63, v63
	v_add_f32_e32 v56, 1.0, v56
	v_add_f32_e32 v57, 1.0, v57
	v_mul_f32_e32 v58, 0xbfb8aa3b, v58
	v_mul_f32_e32 v59, 0xbfb8aa3b, v59
	v_exp_f32_e32 v60, v60
	v_exp_f32_e32 v61, v61
	v_rcp_f32_e32 v56, v56
	v_rcp_f32_e32 v57, v57
	v_exp_f32_e32 v58, v58
	v_exp_f32_e32 v59, v59
	v_mul_f32_e32 v52, 0xbfb8aa3b, v52
	v_mul_f32_e32 v53, 0xbfb8aa3b, v53
	v_exp_f32_e32 v52, v52
	v_exp_f32_e32 v53, v53
	v_mul_f32_e32 v54, 0xbfb8aa3b, v54
	v_mul_f32_e32 v55, 0xbfb8aa3b, v55
	v_exp_f32_e32 v54, v54
	v_exp_f32_e32 v55, v55
	v_mul_f32_e32 v48, 0xbfb8aa3b, v48
	v_mul_f32_e32 v49, 0xbfb8aa3b, v49
	v_add_f32_e32 v60, 1.0, v60
	v_add_f32_e32 v61, 1.0, v61
	v_exp_f32_e32 v48, v48
	v_exp_f32_e32 v49, v49
	v_mul_f32_e32 v50, 0xbfb8aa3b, v50
	v_mul_f32_e32 v51, 0xbfb8aa3b, v51
	v_rcp_f32_e32 v60, v60
	v_rcp_f32_e32 v61, v61
	v_exp_f32_e32 v50, v50
	v_exp_f32_e32 v51, v51
	v_add_f32_e32 v52, 1.0, v52
	v_add_f32_e32 v53, 1.0, v53
	v_mul_f32_e32 v44, 0xbfb8aa3b, v44
	v_mul_f32_e32 v45, 0xbfb8aa3b, v45
	s_waitcnt vmcnt(15)
	v_lshlrev_b32_e32 v130, 16, v112
	v_and_b32_e32 v131, 0xffff0000, v112
	s_waitcnt vmcnt(14)
	v_lshlrev_b32_e32 v132, 16, v116
	v_and_b32_e32 v133, 0xffff0000, v116
	v_lshlrev_b32_e32 v112, 16, v113
	v_and_b32_e32 v113, 0xffff0000, v113
	v_lshlrev_b32_e32 v116, 16, v117
	v_and_b32_e32 v117, 0xffff0000, v117
	v_pk_fma_f32 v[62:63], v[62:63], v[116:117], v[112:113]
	v_lshlrev_b32_e32 v112, 16, v114
	v_and_b32_e32 v113, 0xffff0000, v114
	v_lshlrev_b32_e32 v116, 16, v118
	v_and_b32_e32 v117, 0xffff0000, v118
	v_pk_fma_f32 v[112:113], v[56:57], v[116:117], v[112:113]
	v_add_f32_e32 v56, 1.0, v58
	v_add_f32_e32 v57, 1.0, v59
	v_rcp_f32_e32 v56, v56
	v_rcp_f32_e32 v57, v57
	v_rcp_f32_e32 v52, v52
	v_rcp_f32_e32 v53, v53
	v_add_f32_e32 v54, 1.0, v54
	v_add_f32_e32 v55, 1.0, v55
	v_exp_f32_e32 v44, v44
	v_exp_f32_e32 v45, v45
	v_mul_f32_e32 v46, 0xbfb8aa3b, v46
	v_mul_f32_e32 v47, 0xbfb8aa3b, v47
	v_lshlrev_b32_e32 v58, 16, v115
	v_and_b32_e32 v59, 0xffff0000, v115
	v_lshlrev_b32_e32 v114, 16, v119
	v_and_b32_e32 v115, 0xffff0000, v119
	v_rcp_f32_e32 v54, v54
	v_rcp_f32_e32 v55, v55
	v_add_f32_e32 v48, 1.0, v48
	v_add_f32_e32 v49, 1.0, v49
	v_exp_f32_e32 v46, v46
	v_exp_f32_e32 v47, v47
	v_mul_f32_e32 v40, 0xbfb8aa3b, v40
	v_mul_f32_e32 v41, 0xbfb8aa3b, v41
	v_pk_fma_f32 v[60:61], v[60:61], v[132:133], v[130:131]
	v_pk_fma_f32 v[114:115], v[56:57], v[114:115], v[58:59]
	v_lshl_add_u64 v[56:57], v[128:129], 2, s[38:39]
	v_rcp_f32_e32 v48, v48
	v_rcp_f32_e32 v49, v49
	v_add_f32_e32 v50, 1.0, v50
	v_add_f32_e32 v51, 1.0, v51
	v_exp_f32_e32 v40, v40
	v_exp_f32_e32 v41, v41
	v_mul_f32_e32 v42, 0xbfb8aa3b, v42
	v_mul_f32_e32 v43, 0xbfb8aa3b, v43
	global_store_dwordx4 v[56:57], v[60:63], off
	s_waitcnt vmcnt(14)
; __device__ __forceinline__ float bf_lo(unsigned w) { return __uint_as_float(w << 16); }
; __device__ __forceinline__ float bf_hi(unsigned w) { return __uint_as_float(w & 0xffff0000u); }
; __device__ __forceinline__ float fast_sigmoid(float v) { return __builtin_amdgcn_rcpf(1.0f + __builtin_amdgcn_exp2f(-1.4426950408889634f * v)); }
;     __device__ __forceinline__ void operator()(const Acc& acc, const Unit& u, int wr, int wc, int fr, int fq) const {
;     ...
;                     const f32x4 a0 = acc[ai][bj][m][0], a1 = acc[ai][bj][m][1];
;                     f32x4 r0, r1;
;                     r0[0] = bf_lo(x.x) + fast_sigmoid(a0[0]) * bf_lo(p.x); r0[1] = bf_hi(x.x) + fast_sigmoid(a0[1]) * bf_hi(p.x);
;                     r0[2] = bf_lo(x.y) + fast_sigmoid(a0[2]) * bf_lo(p.y); r0[3] = bf_hi(x.y) + fast_sigmoid(a0[3]) * bf_hi(p.y);
;                     r1[0] = bf_lo(x.z) + fast_sigmoid(a1[0]) * bf_lo(p.z); r1[1] = bf_hi(x.z) + fast_sigmoid(a1[1]) * bf_hi(p.z);
;                     r1[2] = bf_lo(x.w) + fast_sigmoid(a1[2]) * bf_lo(p.w); r1[3] = bf_hi(x.w) + fast_sigmoid(a1[3]) * bf_hi(p.w);
;                     if constexpr (OUT_F32) { *(f32x4*)(outf + o) = r0; *(f32x4*)(outf + o + 4) = r1; }
	v_lshlrev_b32_e32 v58, 16, v120
	v_and_b32_e32 v59, 0xffff0000, v120
	s_waitcnt vmcnt(13)
	v_lshlrev_b32_e32 v60, 16, v124
	v_and_b32_e32 v61, 0xffff0000, v124
	v_rcp_f32_e32 v50, v50
	v_rcp_f32_e32 v51, v51
	v_exp_f32_e32 v42, v42
	v_exp_f32_e32 v43, v43
	v_pk_fma_f32 v[52:53], v[52:53], v[60:61], v[58:59]
	v_lshlrev_b32_e32 v58, 16, v121
	v_and_b32_e32 v59, 0xffff0000, v121
	v_lshlrev_b32_e32 v60, 16, v125
	v_and_b32_e32 v61, 0xffff0000, v125
	v_add_f32_e32 v44, 1.0, v44
	v_add_f32_e32 v45, 1.0, v45
	v_mul_f32_e32 v36, 0xbfb8aa3b, v36
	v_mul_f32_e32 v37, 0xbfb8aa3b, v37
	v_pk_fma_f32 v[54:55], v[54:55], v[60:61], v[58:59]
	v_lshlrev_b32_e32 v58, 16, v122
	v_and_b32_e32 v59, 0xffff0000, v122
	v_lshlrev_b32_e32 v60, 16, v126
	v_and_b32_e32 v61, 0xffff0000, v126
	v_rcp_f32_e32 v44, v44
	v_rcp_f32_e32 v45, v45
	v_add_f32_e32 v46, 1.0, v46
	v_add_f32_e32 v47, 1.0, v47
	v_exp_f32_e32 v36, v36
	v_exp_f32_e32 v37, v37
	v_mul_f32_e32 v38, 0xbfb8aa3b, v38
	v_mul_f32_e32 v39, 0xbfb8aa3b, v39
	v_pk_fma_f32 v[48:49], v[48:49], v[60:61], v[58:59]
	v_lshlrev_b32_e32 v58, 16, v123
	v_and_b32_e32 v59, 0xffff0000, v123
	v_lshlrev_b32_e32 v60, 16, v127
	v_and_b32_e32 v61, 0xffff0000, v127
	v_rcp_f32_e32 v46, v46
	v_rcp_f32_e32 v47, v47
	v_add_f32_e32 v40, 1.0, v40
	v_add_f32_e32 v41, 1.0, v41
	v_exp_f32_e32 v38, v38
	v_exp_f32_e32 v39, v39
	v_mul_f32_e32 v32, 0xbfb8aa3b, v32
	v_mul_f32_e32 v33, 0xbfb8aa3b, v33
	v_pk_fma_f32 v[50:51], v[50:51], v[60:61], v[58:59]
	v_rcp_f32_e32 v40, v40
	v_rcp_f32_e32 v41, v41
	v_add_f32_e32 v42, 1.0, v42
	v_add_f32_e32 v43, 1.0, v43
	v_exp_f32_e32 v32, v32
	v_exp_f32_e32 v33, v33
	v_mul_f32_e32 v34, 0xbfb8aa3b, v34
	v_mul_f32_e32 v35, 0xbfb8aa3b, v35
	global_store_dwordx4 v[56:57], v[48:51], off offset:528
	v_rcp_f32_e32 v42, v42
	v_rcp_f32_e32 v43, v43
	s_waitcnt vmcnt(13)
	v_lshlrev_b32_e32 v48, 16, v104
	v_and_b32_e32 v49, 0xffff0000, v104
	s_waitcnt vmcnt(11)
	v_lshlrev_b32_e32 v50, 16, v108
	v_and_b32_e32 v51, 0xffff0000, v108
	v_exp_f32_e32 v34, v34
	v_exp_f32_e32 v35, v35
	v_pk_fma_f32 v[44:45], v[44:45], v[50:51], v[48:49]
	v_lshlrev_b32_e32 v48, 16, v105
	v_and_b32_e32 v49, 0xffff0000, v105
	v_lshlrev_b32_e32 v50, 16, v109
	v_and_b32_e32 v51, 0xffff0000, v109
	v_add_f32_e32 v36, 1.0, v36
	v_add_f32_e32 v37, 1.0, v37
	v_mul_f32_e32 v28, 0xbfb8aa3b, v28
	v_mul_f32_e32 v29, 0xbfb8aa3b, v29
	v_pk_fma_f32 v[46:47], v[46:47], v[50:51], v[48:49]
	v_lshlrev_b32_e32 v48, 16, v106
	v_and_b32_e32 v49, 0xffff0000, v106
	v_lshlrev_b32_e32 v50, 16, v110
	v_and_b32_e32 v51, 0xffff0000, v110
	v_rcp_f32_e32 v36, v36
	v_rcp_f32_e32 v37, v37
	v_add_f32_e32 v38, 1.0, v38
	v_add_f32_e32 v39, 1.0, v39
	v_exp_f32_e32 v28, v28
	v_exp_f32_e32 v29, v29
	v_mul_f32_e32 v30, 0xbfb8aa3b, v30
	v_mul_f32_e32 v31, 0xbfb8aa3b, v31
	v_pk_fma_f32 v[40:41], v[40:41], v[50:51], v[48:49]
	v_lshlrev_b32_e32 v48, 16, v107
	v_and_b32_e32 v49, 0xffff0000, v107
	v_lshlrev_b32_e32 v50, 16, v111
	v_and_b32_e32 v51, 0xffff0000, v111
	v_rcp_f32_e32 v38, v38
	v_rcp_f32_e32 v39, v39
	v_add_f32_e32 v32, 1.0, v32
	v_add_f32_e32 v33, 1.0, v33
	v_exp_f32_e32 v30, v30
	v_exp_f32_e32 v31, v31
	v_mul_f32_e32 v24, 0xbfb8aa3b, v24
	v_mul_f32_e32 v25, 0xbfb8aa3b, v25
	v_pk_fma_f32 v[42:43], v[42:43], v[50:51], v[48:49]
	v_lshl_add_u64 v[48:49], v[56:57], 0, s[12:13]
	v_rcp_f32_e32 v32, v32
	v_rcp_f32_e32 v33, v33
	v_add_f32_e32 v34, 1.0, v34
	v_add_f32_e32 v35, 1.0, v35
	v_exp_f32_e32 v24, v24
	v_exp_f32_e32 v25, v25
	v_mul_f32_e32 v26, 0xbfb8aa3b, v26
	v_mul_f32_e32 v27, 0xbfb8aa3b, v27
	global_store_dwordx4 v[48:49], v[40:43], off offset:16
	v_rcp_f32_e32 v34, v34
	v_rcp_f32_e32 v35, v35
	v_lshlrev_b32_e32 v40, 16, v100
	v_and_b32_e32 v41, 0xffff0000, v100
	s_waitcnt vmcnt(11)
	v_lshlrev_b32_e32 v42, 16, v96
	v_and_b32_e32 v43, 0xffff0000, v96
	v_exp_f32_e32 v26, v26
	v_exp_f32_e32 v27, v27
	v_pk_fma_f32 v[36:37], v[36:37], v[42:43], v[40:41]
	v_lshlrev_b32_e32 v40, 16, v101
	v_and_b32_e32 v41, 0xffff0000, v101
	v_lshlrev_b32_e32 v42, 16, v97
	v_and_b32_e32 v43, 0xffff0000, v97
	v_add_f32_e32 v28, 1.0, v28
	v_add_f32_e32 v29, 1.0, v29
	v_mul_f32_e32 v20, 0xbfb8aa3b, v20
	v_mul_f32_e32 v21, 0xbfb8aa3b, v21
	v_pk_fma_f32 v[38:39], v[38:39], v[42:43], v[40:41]
	v_lshlrev_b32_e32 v40, 16, v102
	v_and_b32_e32 v41, 0xffff0000, v102
	v_lshlrev_b32_e32 v42, 16, v98
	v_and_b32_e32 v43, 0xffff0000, v98
	v_rcp_f32_e32 v28, v28
	v_rcp_f32_e32 v29, v29
	v_add_f32_e32 v30, 1.0, v30
	v_add_f32_e32 v31, 1.0, v31
	v_exp_f32_e32 v20, v20
	v_exp_f32_e32 v21, v21
	v_mul_f32_e32 v22, 0xbfb8aa3b, v22
	v_mul_f32_e32 v23, 0xbfb8aa3b, v23
	v_pk_fma_f32 v[32:33], v[32:33], v[42:43], v[40:41]
	v_lshlrev_b32_e32 v40, 16, v103
	v_and_b32_e32 v41, 0xffff0000, v103
	v_lshlrev_b32_e32 v42, 16, v99
	v_and_b32_e32 v43, 0xffff0000, v99
	v_rcp_f32_e32 v30, v30
	v_rcp_f32_e32 v31, v31
	v_add_f32_e32 v24, 1.0, v24
	v_add_f32_e32 v25, 1.0, v25
	v_exp_f32_e32 v22, v22
	v_exp_f32_e32 v23, v23
	v_mul_f32_e32 v16, 0xbfb8aa3b, v16
	v_mul_f32_e32 v17, 0xbfb8aa3b, v17
	v_pk_fma_f32 v[34:35], v[34:35], v[42:43], v[40:41]
	v_lshl_add_u64 v[40:41], v[56:57], 0, s[14:15]
	v_rcp_f32_e32 v24, v24
	v_rcp_f32_e32 v25, v25
	v_add_f32_e32 v26, 1.0, v26
	v_add_f32_e32 v27, 1.0, v27
	v_exp_f32_e32 v16, v16
	v_exp_f32_e32 v17, v17
	v_mul_f32_e32 v18, 0xbfb8aa3b, v18
	v_mul_f32_e32 v19, 0xbfb8aa3b, v19
	global_store_dwordx4 v[40:41], v[32:35], off offset:16
	v_rcp_f32_e32 v26, v26
	v_rcp_f32_e32 v27, v27
	s_waitcnt vmcnt(11)
	v_lshlrev_b32_e32 v32, 16, v88
	v_and_b32_e32 v33, 0xffff0000, v88
	s_waitcnt vmcnt(9)
; __device__ __forceinline__ float bf_lo(unsigned w) { return __uint_as_float(w << 16); }
; __device__ __forceinline__ float bf_hi(unsigned w) { return __uint_as_float(w & 0xffff0000u); }
; __device__ __forceinline__ float fast_sigmoid(float v) { return __builtin_amdgcn_rcpf(1.0f + __builtin_amdgcn_exp2f(-1.4426950408889634f * v)); }
; #define PG8_BAR __builtin_amdgcn_s_barrier()
; __device__ __forceinline__ u32x4 pack8(const f32x4 a, const f32x4 b) { u32x4 w; w.x = cvt_pk_bf16(a[0], a[1]); w.y = cvt_pk_bf16(a[2], a[3]); w.z = cvt_pk_bf16(b[0], b[1]); w.w = cvt_pk_bf16(b[2], b[3]); return w; }
; template <class Epi, bool ALIGN_EPI = false, bool SP2 = true>
; __device__ __forceinline__ void gemm_phase(LAS unsigned char* lds, const Gemm g, const StaticOrder& S, const Epi& E) {
;     ...
;         if constexpr (ALIGN_EPI) { if (wr == 0) PG8_BAR; }
;         if constexpr (!Epi::AFTER_DRAIN) E(acc, cur, wr, wc, fr, fq);
;         if (!has_next) break;
; #pragma unroll
;         for (int a = 0; a < 2; ++a)
; #pragma unroll
;             for (int b = 0; b < 2; ++b)
; #pragma unroll
;                 for (int m = 0; m < 4; ++m)
; #pragma unroll
;                     for (int n = 0; n < 2; ++n) acc[a][b][m][n] = (f32x4){0.f, 0.f, 0.f, 0.f};
;         cur = nxt; cA = nA; cB = nB; ++ui;
;         if constexpr (ALIGN_EPI) { if (wr == 1) PG8_BAR; }
;     }
;     __device__ __forceinline__ void operator()(const Acc& acc, const Unit& u, int wr, int wc, int fr, int fq) const {
;     ...
;                     const f32x4 a0 = acc[ai][bj][m][0], a1 = acc[ai][bj][m][1];
;                     f32x4 r0, r1;
;                     r0[0] = bf_lo(x.x) + fast_sigmoid(a0[0]) * bf_lo(p.x); r0[1] = bf_hi(x.x) + fast_sigmoid(a0[1]) * bf_hi(p.x);
;                     r0[2] = bf_lo(x.y) + fast_sigmoid(a0[2]) * bf_lo(p.y); r0[3] = bf_hi(x.y) + fast_sigmoid(a0[3]) * bf_hi(p.y);
;                     r1[0] = bf_lo(x.z) + fast_sigmoid(a1[0]) * bf_lo(p.z); r1[1] = bf_hi(x.z) + fast_sigmoid(a1[1]) * bf_hi(p.z);
;                     r1[2] = bf_lo(x.w) + fast_sigmoid(a1[2]) * bf_lo(p.w); r1[3] = bf_hi(x.w) + fast_sigmoid(a1[3]) * bf_hi(p.w);
;                     if constexpr (OUT_F32) { *(f32x4*)(outf + o) = r0; *(f32x4*)(outf + o + 4) = r1; }
;                     else *(u32x4*)(xb + o) = pack8(r0, r1);
;                 }
	v_lshlrev_b32_e32 v34, 16, v92
	v_and_b32_e32 v35, 0xffff0000, v92
	v_exp_f32_e32 v18, v18
	v_exp_f32_e32 v19, v19
	v_pk_fma_f32 v[28:29], v[28:29], v[34:35], v[32:33]
	v_lshlrev_b32_e32 v32, 16, v89
	v_and_b32_e32 v33, 0xffff0000, v89
	v_lshlrev_b32_e32 v34, 16, v93
	v_and_b32_e32 v35, 0xffff0000, v93
	v_add_f32_e32 v20, 1.0, v20
	v_add_f32_e32 v21, 1.0, v21
	v_mul_f32_e32 v12, 0xbfb8aa3b, v12
	v_mul_f32_e32 v13, 0xbfb8aa3b, v13
	v_pk_fma_f32 v[30:31], v[30:31], v[34:35], v[32:33]
	v_lshlrev_b32_e32 v32, 16, v90
	v_and_b32_e32 v33, 0xffff0000, v90
	v_lshlrev_b32_e32 v34, 16, v94
	v_and_b32_e32 v35, 0xffff0000, v94
	v_rcp_f32_e32 v20, v20
	v_rcp_f32_e32 v21, v21
	v_add_f32_e32 v22, 1.0, v22
	v_add_f32_e32 v23, 1.0, v23
	v_exp_f32_e32 v12, v12
	v_exp_f32_e32 v13, v13
	v_mul_f32_e32 v14, 0xbfb8aa3b, v14
	v_mul_f32_e32 v15, 0xbfb8aa3b, v15
	v_pk_fma_f32 v[24:25], v[24:25], v[34:35], v[32:33]
	v_lshlrev_b32_e32 v32, 16, v91
	v_and_b32_e32 v33, 0xffff0000, v91
	v_lshlrev_b32_e32 v34, 16, v95
	v_and_b32_e32 v35, 0xffff0000, v95
	v_rcp_f32_e32 v22, v22
	v_rcp_f32_e32 v23, v23
	v_add_f32_e32 v16, 1.0, v16
	v_add_f32_e32 v17, 1.0, v17
	v_exp_f32_e32 v14, v14
	v_exp_f32_e32 v15, v15
	v_mul_f32_e32 v8, 0xbfb8aa3b, v8
	v_mul_f32_e32 v9, 0xbfb8aa3b, v9
	v_pk_fma_f32 v[26:27], v[26:27], v[34:35], v[32:33]
	v_lshl_add_u64 v[32:33], v[56:57], 0, s[16:17]
	v_rcp_f32_e32 v16, v16
	v_rcp_f32_e32 v17, v17
	v_add_f32_e32 v18, 1.0, v18
	v_add_f32_e32 v19, 1.0, v19
	v_exp_f32_e32 v8, v8
	v_exp_f32_e32 v9, v9
	v_mul_f32_e32 v10, 0xbfb8aa3b, v10
	v_mul_f32_e32 v11, 0xbfb8aa3b, v11
	global_store_dwordx4 v[32:33], v[24:27], off offset:16
	v_rcp_f32_e32 v18, v18
	v_rcp_f32_e32 v19, v19
	v_lshlrev_b32_e32 v24, 16, v84
	v_and_b32_e32 v25, 0xffff0000, v84
	s_waitcnt vmcnt(9)
	v_lshlrev_b32_e32 v26, 16, v80
	v_and_b32_e32 v27, 0xffff0000, v80
	v_exp_f32_e32 v10, v10
	v_exp_f32_e32 v11, v11
	v_pk_fma_f32 v[20:21], v[20:21], v[26:27], v[24:25]
	v_lshlrev_b32_e32 v24, 16, v85
	v_and_b32_e32 v25, 0xffff0000, v85
	v_lshlrev_b32_e32 v26, 16, v81
	v_and_b32_e32 v27, 0xffff0000, v81
	v_add_f32_e32 v12, 1.0, v12
	v_add_f32_e32 v13, 1.0, v13
	v_mul_f32_e32 v4, 0xbfb8aa3b, v4
	v_mul_f32_e32 v5, 0xbfb8aa3b, v5
	v_pk_fma_f32 v[22:23], v[22:23], v[26:27], v[24:25]
	v_lshlrev_b32_e32 v24, 16, v86
	v_and_b32_e32 v25, 0xffff0000, v86
	v_lshlrev_b32_e32 v26, 16, v82
	v_and_b32_e32 v27, 0xffff0000, v82
	v_rcp_f32_e32 v12, v12
	v_rcp_f32_e32 v13, v13
	v_add_f32_e32 v14, 1.0, v14
	v_add_f32_e32 v15, 1.0, v15
	v_exp_f32_e32 v4, v4
	v_exp_f32_e32 v5, v5
	v_mul_f32_e32 v6, 0xbfb8aa3b, v6
	v_mul_f32_e32 v7, 0xbfb8aa3b, v7
	v_pk_fma_f32 v[16:17], v[16:17], v[26:27], v[24:25]
	v_lshlrev_b32_e32 v24, 16, v87
	v_and_b32_e32 v25, 0xffff0000, v87
	v_lshlrev_b32_e32 v26, 16, v83
	v_and_b32_e32 v27, 0xffff0000, v83
	v_rcp_f32_e32 v14, v14
	v_rcp_f32_e32 v15, v15
	v_add_f32_e32 v8, 1.0, v8
	v_add_f32_e32 v9, 1.0, v9
	v_exp_f32_e32 v6, v6
	v_exp_f32_e32 v7, v7
	v_mul_f32_e32 v0, 0xbfb8aa3b, v0
	v_mul_f32_e32 v1, 0xbfb8aa3b, v1
	v_pk_fma_f32 v[18:19], v[18:19], v[26:27], v[24:25]
	v_lshl_add_u64 v[24:25], v[56:57], 0, s[18:19]
	v_rcp_f32_e32 v8, v8
	v_rcp_f32_e32 v9, v9
	v_add_f32_e32 v10, 1.0, v10
	v_add_f32_e32 v11, 1.0, v11
	v_exp_f32_e32 v0, v0
	v_exp_f32_e32 v1, v1
	v_mul_f32_e32 v2, 0xbfb8aa3b, v2
	v_mul_f32_e32 v3, 0xbfb8aa3b, v3
	global_store_dwordx4 v[24:25], v[16:19], off offset:16
	v_rcp_f32_e32 v10, v10
	v_rcp_f32_e32 v11, v11
	s_waitcnt vmcnt(9)
	v_lshlrev_b32_e32 v16, 16, v72
	v_and_b32_e32 v17, 0xffff0000, v72
	s_waitcnt vmcnt(7)
	v_lshlrev_b32_e32 v18, 16, v76
	v_and_b32_e32 v19, 0xffff0000, v76
	v_exp_f32_e32 v2, v2
	v_exp_f32_e32 v3, v3
	v_pk_fma_f32 v[12:13], v[12:13], v[18:19], v[16:17]
	v_lshlrev_b32_e32 v16, 16, v73
	v_and_b32_e32 v17, 0xffff0000, v73
	v_lshlrev_b32_e32 v18, 16, v77
	v_and_b32_e32 v19, 0xffff0000, v77
	v_add_f32_e32 v4, 1.0, v4
	v_add_f32_e32 v5, 1.0, v5
	v_add_co_u32_e32 v50, vcc, s59, v56
	v_pk_fma_f32 v[14:15], v[14:15], v[18:19], v[16:17]
	v_lshlrev_b32_e32 v16, 16, v74
	v_and_b32_e32 v17, 0xffff0000, v74
	v_lshlrev_b32_e32 v18, 16, v78
	v_and_b32_e32 v19, 0xffff0000, v78
	v_rcp_f32_e32 v4, v4
	v_rcp_f32_e32 v5, v5
	v_add_f32_e32 v6, 1.0, v6
	v_add_f32_e32 v7, 1.0, v7
	v_addc_co_u32_e32 v51, vcc, 0, v57, vcc
	v_pk_fma_f32 v[8:9], v[8:9], v[18:19], v[16:17]
	v_lshlrev_b32_e32 v16, 16, v75
	v_and_b32_e32 v17, 0xffff0000, v75
	v_lshlrev_b32_e32 v18, 16, v79
	v_and_b32_e32 v19, 0xffff0000, v79
	v_rcp_f32_e32 v6, v6
	v_rcp_f32_e32 v7, v7
	v_add_f32_e32 v0, 1.0, v0
	v_add_f32_e32 v1, 1.0, v1
	v_add_co_u32_e32 v34, vcc, s61, v56
	v_pk_fma_f32 v[10:11], v[10:11], v[18:19], v[16:17]
	v_lshl_add_u64 v[16:17], v[56:57], 0, s[20:21]
	v_rcp_f32_e32 v0, v0
	v_rcp_f32_e32 v1, v1
	v_add_f32_e32 v2, 1.0, v2
	v_add_f32_e32 v3, 1.0, v3
	v_addc_co_u32_e32 v35, vcc, 0, v57, vcc
	global_store_dwordx4 v[16:17], v[8:11], off offset:16
	v_rcp_f32_e32 v2, v2
	v_rcp_f32_e32 v3, v3
	v_lshlrev_b32_e32 v8, 16, v64
	v_and_b32_e32 v9, 0xffff0000, v64
	s_waitcnt vmcnt(7)
	v_lshlrev_b32_e32 v10, 16, v68
	v_and_b32_e32 v11, 0xffff0000, v68
	v_add_co_u32_e32 v18, vcc, s62, v56
	v_pk_fma_f32 v[4:5], v[4:5], v[10:11], v[8:9]
	v_lshlrev_b32_e32 v8, 16, v65
	v_and_b32_e32 v9, 0xffff0000, v65
	v_lshlrev_b32_e32 v10, 16, v69
	v_and_b32_e32 v11, 0xffff0000, v69
	v_addc_co_u32_e32 v19, vcc, 0, v57, vcc
	v_pk_fma_f32 v[6:7], v[6:7], v[10:11], v[8:9]
	v_lshlrev_b32_e32 v8, 16, v66
	v_and_b32_e32 v9, 0xffff0000, v66
	v_lshlrev_b32_e32 v10, 16, v70
	v_and_b32_e32 v11, 0xffff0000, v70
	v_pk_fma_f32 v[0:1], v[0:1], v[10:11], v[8:9]
	v_lshlrev_b32_e32 v8, 16, v67
	v_and_b32_e32 v9, 0xffff0000, v67
	v_lshlrev_b32_e32 v10, 16, v71
	v_and_b32_e32 v11, 0xffff0000, v71
	s_andn2_b64 vcc, exec, s[0:1]
	s_mov_b64 s[0:1], -1
	global_store_dwordx4 v[56:57], v[112:115], off offset:16
	global_store_dwordx4 v[56:57], v[52:55], off offset:512
	global_store_dwordx4 v[50:51], v[44:47], off
	global_store_dwordx4 v[50:51], v[36:39], off offset:512
	global_store_dwordx4 v[34:35], v[28:31], off
	global_store_dwordx4 v[34:35], v[20:23], off offset:512
	global_store_dwordx4 v[18:19], v[12:15], off
	v_pk_fma_f32 v[2:3], v[2:3], v[10:11], v[8:9]
	v_lshl_add_u64 v[8:9], v[56:57], 0, s[24:25]
	global_store_dwordx4 v[18:19], v[4:7], off offset:512
	global_store_dwordx4 v[8:9], v[0:3], off offset:16
	s_cbranch_vccnz .LBB0_847
	s_andn2_b64 vcc, exec, s[4:5]
	s_cbranch_vccnz .LBB0_846
	s_barrier
	s_branch .LBB0_846

; __global__ void __launch_bounds__(NTHREADS, 2) mk_fwd(Params P) {
	.amdhsa_kernel _Z6mk_fwd6Params
		.amdhsa_group_segment_fixed_size 0
		.amdhsa_private_segment_fixed_size 0
		.amdhsa_kernarg_size 384
		.amdhsa_user_sgpr_count 2
		.amdhsa_user_sgpr_dispatch_ptr 0
		.amdhsa_user_sgpr_queue_ptr 0
		.amdhsa_user_sgpr_kernarg_segment_ptr 1
		.amdhsa_user_sgpr_dispatch_id 0
		.amdhsa_user_sgpr_kernarg_preload_length 0
		.amdhsa_user_sgpr_kernarg_preload_offset 0
		.amdhsa_user_sgpr_private_segment_size 0
		.amdhsa_uses_dynamic_stack 0
		.amdhsa_enable_private_segment 0
		.amdhsa_system_sgpr_workgroup_id_x 1
		.amdhsa_system_sgpr_workgroup_id_y 0
		.amdhsa_system_sgpr_workgroup_id_z 0
		.amdhsa_system_sgpr_workgroup_info 0
		.amdhsa_system_vgpr_workitem_id 2
		.amdhsa_next_free_vgpr 256
		.amdhsa_next_free_sgpr 102
		.amdhsa_accum_offset 256
		.amdhsa_reserve_vcc 1
		.amdhsa_float_round_mode_32 0
		.amdhsa_float_round_mode_16_64 0
		.amdhsa_float_denorm_mode_32 3
		.amdhsa_float_denorm_mode_16_64 3
		.amdhsa_dx10_clamp 1
		.amdhsa_ieee_mode 1
		.amdhsa_fp16_overflow 0
		.amdhsa_tg_split 0
		.amdhsa_exception_fp_ieee_invalid_op 0
		.amdhsa_exception_fp_denorm_src 0
		.amdhsa_exception_fp_ieee_div_zero 0
		.amdhsa_exception_fp_ieee_overflow 0
		.amdhsa_exception_fp_ieee_underflow 0
		.amdhsa_exception_fp_ieee_inexact 0
		.amdhsa_exception_int_div_zero 0
	.end_amdhsa_kernel

; __global__ void __launch_bounds__(NTHREADS, 2) mk_fwd(Params P) {
amdhsa.kernels:
  - .agpr_count:     0
    .args:
      - .offset:         0
        .size:           128
        .value_kind:     by_value
      - .offset:         128
        .size:           4
        .value_kind:     hidden_block_count_x
      - .offset:         132
        .size:           4
        .value_kind:     hidden_block_count_y
      - .offset:         136
        .size:           4
        .value_kind:     hidden_block_count_z
      - .offset:         140
        .size:           2
        .value_kind:     hidden_group_size_x
      - .offset:         142
        .size:           2
        .value_kind:     hidden_group_size_y
      - .offset:         144
        .size:           2
        .value_kind:     hidden_group_size_z
      - .offset:         146
        .size:           2
        .value_kind:     hidden_remainder_x
      - .offset:         148
        .size:           2
        .value_kind:     hidden_remainder_y
      - .offset:         150
        .size:           2
        .value_kind:     hidden_remainder_z
      - .offset:         168
        .size:           8
        .value_kind:     hidden_global_offset_x
      - .offset:         176
        .size:           8
        .value_kind:     hidden_global_offset_y
      - .offset:         184
        .size:           8
        .value_kind:     hidden_global_offset_z
      - .offset:         192
        .size:           2
        .value_kind:     hidden_grid_dims
      - .offset:         216
        .size:           8
        .value_kind:     hidden_multigrid_sync_arg
      - .offset:         248
        .size:           4
        .value_kind:     hidden_dynamic_lds_size
    .group_segment_fixed_size: 0
    .kernarg_segment_align: 8
    .kernarg_segment_size: 384
    .language:       OpenCL C
    .language_version:
      - 2
      - 0
    .max_flat_workgroup_size: 512
    .name:           _Z6mk_fwd6Params
    .private_segment_fixed_size: 0
    .sgpr_count:     108
    .sgpr_spill_count: 0
    .symbol:         _Z6mk_fwd6Params.kd
    .uniform_work_group_size: 1
    .uses_dynamic_stack: false
    .vgpr_count:     256
    .vgpr_spill_count: 0
    .wavefront_size: 64
